# GEMM K-loops without per-segment priority flips; one static priority raise for waves 4-7 during the in-projection GEMM
# baseline (speedup 1.0000x reference)
; template <class Epi, class Sched, bool ALIGN_EPI = false, bool SP2 = false>
; __device__ __forceinline__ void gemm_phase(PG8_LAS unsigned char* lds, const Gemm g, const Sched& S, const Epi& E) {
;     ...
;     const int tid = tid_, wid = __builtin_amdgcn_readfirstlane(tid >> 6), lane = tid & 63, wr = wid >> 2, wc = wid & 3, fr = lane & 15, fq = lane >> 4;
.LBB0_117:
	s_cmp_eq_u32 s5, 1
	s_cbranch_scc0 .Lp1_noprio
	s_setprio 1

; #define PG8_STAGE(bufoff, gbase, voff) do { _Pragma("unroll") for (int _i = 0; _i < 2; ++_i) \
;         __builtin_amdgcn_global_load_lds((const unsigned*)((const char*)(gbase) + (voff)[_i]), (PG8_LAS unsigned*)(lds + (bufoff) + ldsw + _i * 8192), 16, 0, 0); } while (0)
; #define PG8_LDA(dst, b, h) do { _Pragma("unroll") for (int m = 0; m < 4; ++m) _Pragma("unroll") for (int k = 0; k < 2; ++k) dst[m][k] = *(const PG8_LAS bf16x8*)(lds + PG8_SA(b, h) + aoff + m * 2048 + k * 1024); } while (0)
; #define PG8_LDB(dst, b, h) do { _Pragma("unroll") for (int n = 0; n < 2; ++n) _Pragma("unroll") for (int k = 0; k < 2; ++k) dst[n][k] = *(const PG8_LAS bf16x8*)(lds + PG8_SB(b, h) + boff + n * 2048 + k * 1024); } while (0)
; #define PG8_MMA(ai, bj, At, Bt) do { __builtin_amdgcn_s_setprio(1); _Pragma("unroll") for (int m = 0; m < 4; ++m) _Pragma("unroll") for (int n = 0; n < 2; ++n) _Pragma("unroll") for (int k = 0; k < 2; ++k) \
;         acc[ai][bj][m][n] = __builtin_amdgcn_mfma_f32_16x16x32_bf16(Bt[n][k], At[m][k], acc[ai][bj][m][n], 0, 0, 0); __builtin_amdgcn_s_setprio(0); } while (0)
; #define PG8_WAIT_V(n) asm volatile("s_waitcnt vmcnt(" #n ")" ::: "memory")
; #define PG8_WAIT_L(n) asm volatile("s_waitcnt lgkmcnt(" #n ")" ::: "memory")
; #define PG8_BAR __builtin_amdgcn_s_barrier()
; template <class Epi, class Sched, bool ALIGN_EPI = false, bool SP2 = false>
; __device__ __forceinline__ void gemm_phase(PG8_LAS unsigned char* lds, const Gemm g, const Sched& S, const Epi& E) {
;     ...
;             const char* a1 = cA + (size_t)(t + 1) * kstep;
;             const char* a2 = last ? nA : cA + (size_t)(t + 2) * kstep; const char* b2 = last ? nB : cB + (size_t)(t + 2) * kstep;
;             const char* a3 = a2 + kstep; const char* b3 = b2 + kstep;
;             if (last && has_next) S.a_ready(nxt);
;             if constexpr (SP2) {
;             PG8_LDB(B0, 0, 0); PG8_LDB(B1, 0, 1); PG8_SCHED; PG8_LDA(At, 0, 0); PG8_STAGE(PG8_SA(1, 1), a1 + hstep, voffA);
;             PG8_WAIT_V(8); PG8_WAIT_L(0); PG8_BAR; PG8_MMA(0, 0, At, B0); PG8_MMA(0, 1, At, B1); PG8_BAR; PG8_SCHED;
;             PG8_LDA(At, 0, 1); PG8_STAGE(PG8_SB(0, 0), b2, voffB); PG8_STAGE(PG8_SB(0, 1), b2 + hstep, voffB); PG8_STAGE(PG8_SA(0, 0), a2, voffA);
;             PG8_WAIT_V(8); PG8_WAIT_L(0); PG8_BAR; PG8_MMA(1, 0, At, B0); PG8_MMA(1, 1, At, B1); PG8_BAR; PG8_SCHED;
.LBB0_123:
	s_add_u32 s8, s6, 0xfff80080
	s_addc_u32 s9, s7, -1
	s_add_i32 s43, 0, 0x10000
	s_cmp_eq_u32 s42, 28
	s_cselect_b32 s23, s15, s9
	s_cselect_b32 s22, s24, s8
	s_cselect_b32 s9, s17, s41
	s_cselect_b32 s8, s25, s40
	s_add_i32 s48, 0, 0x14000
	v_add_u32_e32 v172, s43, v165
	v_add_u32_e32 v188, s48, v165
	ds_read_b128 v[156:159], v172
	ds_read_b128 v[160:163], v172 offset:1024
	ds_read_b128 v[168:171], v172 offset:2048
	ds_read_b128 v[172:175], v172 offset:3072
	ds_read_b128 v[176:179], v188
	ds_read_b128 v[180:183], v188 offset:1024
	ds_read_b128 v[184:187], v188 offset:2048
	ds_read_b128 v[188:191], v188 offset:3072
	v_lshl_add_u64 v[228:229], s[6:7], 0, v[152:153]
	s_add_i32 m0, s31, 0xc000
	ds_read_b128 v[192:195], v167
	ds_read_b128 v[196:199], v167 offset:1024
	ds_read_b128 v[200:203], v167 offset:2048
	ds_read_b128 v[204:207], v167 offset:3072
	ds_read_b128 v[208:211], v167 offset:4096
	ds_read_b128 v[212:215], v167 offset:5120
	ds_read_b128 v[216:219], v167 offset:6144
	ds_read_b128 v[224:227], v167 offset:7168
	global_load_lds_dwordx4 v[228:229], off
	s_add_i32 m0, s31, 0xe000
	v_lshl_add_u64 v[228:229], s[6:7], 0, v[154:155]
	global_load_lds_dwordx4 v[228:229], off
	s_waitcnt vmcnt(8) lgkmcnt(0)
	s_barrier
	v_mfma_f32_16x16x32_bf16 v[144:147], v[156:159], v[192:195], v[144:147]
	v_mfma_f32_16x16x32_bf16 v[122:125], v[168:171], v[192:195], v[122:125]
	v_mfma_f32_16x16x32_bf16 v[110:113], v[156:159], v[200:203], v[110:113]
	v_mfma_f32_16x16x32_bf16 v[106:109], v[168:171], v[200:203], v[106:109]
	v_mfma_f32_16x16x32_bf16 v[94:97], v[156:159], v[208:211], v[94:97]
	v_mfma_f32_16x16x32_bf16 v[90:93], v[168:171], v[208:211], v[90:93]
	v_mfma_f32_16x16x32_bf16 v[78:81], v[156:159], v[216:219], v[78:81]
	v_mfma_f32_16x16x32_bf16 v[74:77], v[168:171], v[216:219], v[74:77]
	v_mfma_f32_16x16x32_bf16 v[144:147], v[160:163], v[196:199], v[144:147]
	v_mfma_f32_16x16x32_bf16 v[122:125], v[172:175], v[196:199], v[122:125]
	v_mfma_f32_16x16x32_bf16 v[110:113], v[160:163], v[204:207], v[110:113]
	v_mfma_f32_16x16x32_bf16 v[106:109], v[172:175], v[204:207], v[106:109]
	v_mfma_f32_16x16x32_bf16 v[94:97], v[160:163], v[212:215], v[94:97]
	v_mfma_f32_16x16x32_bf16 v[90:93], v[172:175], v[212:215], v[90:93]
	v_mfma_f32_16x16x32_bf16 v[78:81], v[160:163], v[224:227], v[78:81]
	v_mfma_f32_16x16x32_bf16 v[74:77], v[172:175], v[224:227], v[74:77]
	v_mfma_f32_16x16x32_bf16 v[118:121], v[176:179], v[192:195], v[118:121]
	v_mfma_f32_16x16x32_bf16 v[114:117], v[184:187], v[192:195], v[114:117]
	v_mfma_f32_16x16x32_bf16 v[102:105], v[176:179], v[200:203], v[102:105]
	v_mfma_f32_16x16x32_bf16 v[98:101], v[184:187], v[200:203], v[98:101]
	v_mfma_f32_16x16x32_bf16 v[86:89], v[176:179], v[208:211], v[86:89]
	v_mfma_f32_16x16x32_bf16 v[82:85], v[184:187], v[208:211], v[82:85]
	v_mfma_f32_16x16x32_bf16 v[70:73], v[176:179], v[216:219], v[70:73]
	v_mfma_f32_16x16x32_bf16 v[66:69], v[184:187], v[216:219], v[66:69]
	v_mfma_f32_16x16x32_bf16 v[118:121], v[180:183], v[196:199], v[118:121]
	v_mfma_f32_16x16x32_bf16 v[114:117], v[188:191], v[196:199], v[114:117]
	v_mfma_f32_16x16x32_bf16 v[102:105], v[180:183], v[204:207], v[102:105]
	v_mfma_f32_16x16x32_bf16 v[98:101], v[188:191], v[204:207], v[98:101]
	v_mfma_f32_16x16x32_bf16 v[86:89], v[180:183], v[212:215], v[86:89]
	v_mfma_f32_16x16x32_bf16 v[82:85], v[188:191], v[212:215], v[82:85]
	v_mfma_f32_16x16x32_bf16 v[70:73], v[180:183], v[224:227], v[70:73]
	v_mfma_f32_16x16x32_bf16 v[66:69], v[188:191], v[224:227], v[66:69]
	s_barrier
	s_add_i32 s43, s43, s30
	v_lshl_add_u64 v[228:229], s[8:9], 0, v[0:1]
	s_mov_b32 m0, s43
	ds_read_b128 v[192:195], v167 offset:16384
	ds_read_b128 v[196:199], v167 offset:17408
	ds_read_b128 v[200:203], v167 offset:18432
	ds_read_b128 v[204:207], v167 offset:19456
	ds_read_b128 v[208:211], v167 offset:20480
	ds_read_b128 v[212:215], v167 offset:21504
	ds_read_b128 v[216:219], v167 offset:22528
	ds_read_b128 v[224:227], v167 offset:23552
	global_load_lds_dwordx4 v[228:229], off
	s_add_i32 m0, s43, 0x2000
	s_add_u32 s82, s8, 0x80000
	v_lshl_add_u64 v[230:231], s[8:9], 0, v[126:127]
	s_addc_u32 s83, s9, 0
	s_add_i32 s43, s48, s30
	global_load_lds_dwordx4 v[230:231], off
	v_lshl_add_u64 v[232:233], s[82:83], 0, v[0:1]
	s_mov_b32 m0, s43
	v_lshl_add_u64 v[244:245], s[22:23], 0, v[148:149]
	global_load_lds_dwordx4 v[232:233], off
	s_add_i32 m0, s43, 0x2000
	v_lshl_add_u64 v[232:233], s[82:83], 0, v[126:127]
	global_load_lds_dwordx4 v[232:233], off
	s_mov_b32 m0, s31
	v_lshl_add_u64 v[232:233], s[22:23], 0, v[150:151]
	global_load_lds_dwordx4 v[232:233], off
	s_mov_b32 m0, s34
	s_nop 0
	global_load_lds_dwordx4 v[244:245], off
	s_waitcnt vmcnt(8) lgkmcnt(0)
	s_barrier
; #define PG8_STAGE(bufoff, gbase, voff) do { _Pragma("unroll") for (int _i = 0; _i < 2; ++_i) \
;         __builtin_amdgcn_global_load_lds((const unsigned*)((const char*)(gbase) + (voff)[_i]), (PG8_LAS unsigned*)(lds + (bufoff) + ldsw + _i * 8192), 16, 0, 0); } while (0)
; #define PG8_LDA(dst, b, h) do { _Pragma("unroll") for (int m = 0; m < 4; ++m) _Pragma("unroll") for (int k = 0; k < 2; ++k) dst[m][k] = *(const PG8_LAS bf16x8*)(lds + PG8_SA(b, h) + aoff + m * 2048 + k * 1024); } while (0)
; #define PG8_LDB(dst, b, h) do { _Pragma("unroll") for (int n = 0; n < 2; ++n) _Pragma("unroll") for (int k = 0; k < 2; ++k) dst[n][k] = *(const PG8_LAS bf16x8*)(lds + PG8_SB(b, h) + boff + n * 2048 + k * 1024); } while (0)
; #define PG8_MMA(ai, bj, At, Bt) do { __builtin_amdgcn_s_setprio(1); _Pragma("unroll") for (int m = 0; m < 4; ++m) _Pragma("unroll") for (int n = 0; n < 2; ++n) _Pragma("unroll") for (int k = 0; k < 2; ++k) \
;         acc[ai][bj][m][n] = __builtin_amdgcn_mfma_f32_16x16x32_bf16(Bt[n][k], At[m][k], acc[ai][bj][m][n], 0, 0, 0); __builtin_amdgcn_s_setprio(0); } while (0)
; #define PG8_WAIT_V(n) asm volatile("s_waitcnt vmcnt(" #n ")" ::: "memory")
; #define PG8_WAIT_L(n) asm volatile("s_waitcnt lgkmcnt(" #n ")" ::: "memory")
; #define PG8_BAR __builtin_amdgcn_s_barrier()
; #define PG8_SCHED __builtin_amdgcn_sched_barrier(0)
; template <class Epi, class Sched, bool ALIGN_EPI = false, bool SP2 = false>
; __device__ __forceinline__ void gemm_phase(PG8_LAS unsigned char* lds, const Gemm g, const Sched& S, const Epi& E) {
;     ...
;             PG8_WAIT_V(8); PG8_WAIT_L(0); PG8_BAR; PG8_MMA(0, 0, At, B0); PG8_MMA(0, 1, At, B1); PG8_BAR; PG8_SCHED;
;             PG8_LDA(At, 0, 1); PG8_STAGE(PG8_SB(0, 0), b2, voffB); PG8_STAGE(PG8_SB(0, 1), b2 + hstep, voffB); PG8_STAGE(PG8_SA(0, 0), a2, voffA);
;             PG8_WAIT_V(8); PG8_WAIT_L(0); PG8_BAR; PG8_MMA(1, 0, At, B0); PG8_MMA(1, 1, At, B1); PG8_BAR; PG8_SCHED;
;             PG8_LDB(B0, 1, 0); PG8_LDB(B1, 1, 1); PG8_SCHED; PG8_LDA(At, 1, 0); PG8_STAGE(PG8_SA(0, 1), a2 + hstep, voffA);
;             PG8_WAIT_V(8); PG8_WAIT_L(0); PG8_BAR; PG8_MMA(0, 0, At, B0); PG8_MMA(0, 1, At, B1); PG8_BAR; PG8_SCHED;
	v_mfma_f32_16x16x32_bf16 v[62:65], v[156:159], v[192:195], v[62:65]
	v_mfma_f32_16x16x32_bf16 v[58:61], v[168:171], v[192:195], v[58:61]
	v_mfma_f32_16x16x32_bf16 v[46:49], v[156:159], v[200:203], v[46:49]
	v_mfma_f32_16x16x32_bf16 v[42:45], v[168:171], v[200:203], v[42:45]
	v_mfma_f32_16x16x32_bf16 v[30:33], v[156:159], v[208:211], v[30:33]
	v_mfma_f32_16x16x32_bf16 v[26:29], v[168:171], v[208:211], v[26:29]
	v_mfma_f32_16x16x32_bf16 v[14:17], v[156:159], v[216:219], v[14:17]
	v_mfma_f32_16x16x32_bf16 v[10:13], v[168:171], v[216:219], v[10:13]
	v_mfma_f32_16x16x32_bf16 v[62:65], v[160:163], v[196:199], v[62:65]
	v_mfma_f32_16x16x32_bf16 v[58:61], v[172:175], v[196:199], v[58:61]
	v_mfma_f32_16x16x32_bf16 v[46:49], v[160:163], v[204:207], v[46:49]
	v_mfma_f32_16x16x32_bf16 v[42:45], v[172:175], v[204:207], v[42:45]
	v_mfma_f32_16x16x32_bf16 v[30:33], v[160:163], v[212:215], v[30:33]
	v_mfma_f32_16x16x32_bf16 v[26:29], v[172:175], v[212:215], v[26:29]
	v_mfma_f32_16x16x32_bf16 v[14:17], v[160:163], v[224:227], v[14:17]
	v_mfma_f32_16x16x32_bf16 v[10:13], v[172:175], v[224:227], v[10:13]
	v_mfma_f32_16x16x32_bf16 v[54:57], v[176:179], v[192:195], v[54:57]
	v_mfma_f32_16x16x32_bf16 v[50:53], v[184:187], v[192:195], v[50:53]
	v_mfma_f32_16x16x32_bf16 v[38:41], v[176:179], v[200:203], v[38:41]
	v_mfma_f32_16x16x32_bf16 v[34:37], v[184:187], v[200:203], v[34:37]
	v_mfma_f32_16x16x32_bf16 v[22:25], v[176:179], v[208:211], v[22:25]
	v_mfma_f32_16x16x32_bf16 v[18:21], v[184:187], v[208:211], v[18:21]
	v_mfma_f32_16x16x32_bf16 v[6:9], v[176:179], v[216:219], v[6:9]
	v_mfma_f32_16x16x32_bf16 v[2:5], v[184:187], v[216:219], v[2:5]
	v_mfma_f32_16x16x32_bf16 v[54:57], v[180:183], v[196:199], v[54:57]
	v_mfma_f32_16x16x32_bf16 v[50:53], v[188:191], v[196:199], v[50:53]
	v_mfma_f32_16x16x32_bf16 v[38:41], v[180:183], v[204:207], v[38:41]
	v_mfma_f32_16x16x32_bf16 v[34:37], v[188:191], v[204:207], v[34:37]
	v_mfma_f32_16x16x32_bf16 v[22:25], v[180:183], v[212:215], v[22:25]
	v_mfma_f32_16x16x32_bf16 v[18:21], v[188:191], v[212:215], v[18:21]
	v_mfma_f32_16x16x32_bf16 v[6:9], v[180:183], v[224:227], v[6:9]
	v_mfma_f32_16x16x32_bf16 v[2:5], v[188:191], v[224:227], v[2:5]
	s_barrier
	s_add_i32 s43, 0, 0x18000
	s_add_i32 s48, 0, 0x1c000
	v_add_u32_e32 v172, s43, v165
	v_add_u32_e32 v188, s48, v165
	ds_read_b128 v[156:159], v172
	ds_read_b128 v[160:163], v172 offset:1024
	ds_read_b128 v[168:171], v172 offset:2048
	ds_read_b128 v[172:175], v172 offset:3072
	ds_read_b128 v[176:179], v188
	ds_read_b128 v[180:183], v188 offset:1024
	ds_read_b128 v[184:187], v188 offset:2048
	ds_read_b128 v[188:191], v188 offset:3072
	s_add_u32 s22, s22, 0x80000
	s_addc_u32 s23, s23, 0
	s_mov_b32 m0, s35
	v_lshl_add_u64 v[246:247], s[22:23], 0, v[150:151]
	ds_read_b128 v[192:195], v167 offset:32768
	ds_read_b128 v[196:199], v167 offset:33792
	ds_read_b128 v[200:203], v167 offset:34816
	ds_read_b128 v[204:207], v167 offset:35840
	ds_read_b128 v[208:211], v167 offset:36864
	ds_read_b128 v[212:215], v167 offset:37888
	ds_read_b128 v[216:219], v167 offset:38912
	ds_read_b128 v[224:227], v167 offset:39936
	global_load_lds_dwordx4 v[246:247], off
	s_mov_b32 m0, s36
	v_lshl_add_u64 v[246:247], s[22:23], 0, v[148:149]
	global_load_lds_dwordx4 v[246:247], off
	s_waitcnt vmcnt(8) lgkmcnt(0)
	s_barrier
	v_mfma_f32_16x16x32_bf16 v[144:147], v[156:159], v[192:195], v[144:147]
	v_mfma_f32_16x16x32_bf16 v[122:125], v[168:171], v[192:195], v[122:125]
	v_mfma_f32_16x16x32_bf16 v[110:113], v[156:159], v[200:203], v[110:113]
	v_mfma_f32_16x16x32_bf16 v[106:109], v[168:171], v[200:203], v[106:109]
	v_mfma_f32_16x16x32_bf16 v[94:97], v[156:159], v[208:211], v[94:97]
	v_mfma_f32_16x16x32_bf16 v[90:93], v[168:171], v[208:211], v[90:93]
	v_mfma_f32_16x16x32_bf16 v[78:81], v[156:159], v[216:219], v[78:81]
	v_mfma_f32_16x16x32_bf16 v[74:77], v[168:171], v[216:219], v[74:77]
	v_mfma_f32_16x16x32_bf16 v[144:147], v[160:163], v[196:199], v[144:147]
	v_mfma_f32_16x16x32_bf16 v[122:125], v[172:175], v[196:199], v[122:125]
	v_mfma_f32_16x16x32_bf16 v[110:113], v[160:163], v[204:207], v[110:113]
	v_mfma_f32_16x16x32_bf16 v[106:109], v[172:175], v[204:207], v[106:109]
	v_mfma_f32_16x16x32_bf16 v[94:97], v[160:163], v[212:215], v[94:97]
	v_mfma_f32_16x16x32_bf16 v[90:93], v[172:175], v[212:215], v[90:93]
	v_mfma_f32_16x16x32_bf16 v[78:81], v[160:163], v[224:227], v[78:81]
	v_mfma_f32_16x16x32_bf16 v[74:77], v[172:175], v[224:227], v[74:77]
	v_mfma_f32_16x16x32_bf16 v[118:121], v[176:179], v[192:195], v[118:121]
	v_mfma_f32_16x16x32_bf16 v[114:117], v[184:187], v[192:195], v[114:117]
	v_mfma_f32_16x16x32_bf16 v[102:105], v[176:179], v[200:203], v[102:105]
	v_mfma_f32_16x16x32_bf16 v[98:101], v[184:187], v[200:203], v[98:101]
	v_mfma_f32_16x16x32_bf16 v[86:89], v[176:179], v[208:211], v[86:89]
	v_mfma_f32_16x16x32_bf16 v[82:85], v[184:187], v[208:211], v[82:85]
	v_mfma_f32_16x16x32_bf16 v[70:73], v[176:179], v[216:219], v[70:73]
	v_mfma_f32_16x16x32_bf16 v[66:69], v[184:187], v[216:219], v[66:69]
	v_mfma_f32_16x16x32_bf16 v[118:121], v[180:183], v[196:199], v[118:121]
	v_mfma_f32_16x16x32_bf16 v[114:117], v[188:191], v[196:199], v[114:117]
	v_mfma_f32_16x16x32_bf16 v[102:105], v[180:183], v[204:207], v[102:105]
	v_mfma_f32_16x16x32_bf16 v[98:101], v[188:191], v[204:207], v[98:101]
	v_mfma_f32_16x16x32_bf16 v[86:89], v[180:183], v[212:215], v[86:89]
	v_mfma_f32_16x16x32_bf16 v[82:85], v[188:191], v[212:215], v[82:85]
	v_mfma_f32_16x16x32_bf16 v[70:73], v[180:183], v[224:227], v[70:73]
	v_mfma_f32_16x16x32_bf16 v[66:69], v[188:191], v[224:227], v[66:69]
	s_barrier
; #define PG8_STAGE(bufoff, gbase, voff) do { _Pragma("unroll") for (int _i = 0; _i < 2; ++_i) \
;         __builtin_amdgcn_global_load_lds((const unsigned*)((const char*)(gbase) + (voff)[_i]), (PG8_LAS unsigned*)(lds + (bufoff) + ldsw + _i * 8192), 16, 0, 0); } while (0)
; #define PG8_LDA(dst, b, h) do { _Pragma("unroll") for (int m = 0; m < 4; ++m) _Pragma("unroll") for (int k = 0; k < 2; ++k) dst[m][k] = *(const PG8_LAS bf16x8*)(lds + PG8_SA(b, h) + aoff + m * 2048 + k * 1024); } while (0)
; #define PG8_MMA(ai, bj, At, Bt) do { __builtin_amdgcn_s_setprio(1); _Pragma("unroll") for (int m = 0; m < 4; ++m) _Pragma("unroll") for (int n = 0; n < 2; ++n) _Pragma("unroll") for (int k = 0; k < 2; ++k) \
;         acc[ai][bj][m][n] = __builtin_amdgcn_mfma_f32_16x16x32_bf16(Bt[n][k], At[m][k], acc[ai][bj][m][n], 0, 0, 0); __builtin_amdgcn_s_setprio(0); } while (0)
; #define PG8_WAIT_V(n) asm volatile("s_waitcnt vmcnt(" #n ")" ::: "memory")
; #define PG8_WAIT_L(n) asm volatile("s_waitcnt lgkmcnt(" #n ")" ::: "memory")
; #define PG8_BAR __builtin_amdgcn_s_barrier()
; #define PG8_SCHED __builtin_amdgcn_sched_barrier(0)
; template <class Epi, class Sched, bool ALIGN_EPI = false, bool SP2 = false>
; __device__ __forceinline__ void gemm_phase(PG8_LAS unsigned char* lds, const Gemm g, const Sched& S, const Epi& E) {
;     ...
;         for (int t = 0; t < nt; t += 2) {
;     ...
;             PG8_WAIT_V(8); PG8_WAIT_L(0); PG8_BAR; PG8_MMA(0, 0, At, B0); PG8_MMA(0, 1, At, B1); PG8_BAR; PG8_SCHED;
;             PG8_LDA(At, 1, 1); PG8_STAGE(PG8_SB(1, 0), b3, voffB); PG8_STAGE(PG8_SB(1, 1), b3 + hstep, voffB); PG8_STAGE(PG8_SA(1, 0), a3, voffA);
;             PG8_WAIT_V(8); PG8_WAIT_L(0); PG8_BAR; PG8_MMA(1, 0, At, B0); PG8_MMA(1, 1, At, B1); PG8_BAR; PG8_SCHED;
	s_add_i32 s22, s43, s30
	v_lshl_add_u64 v[228:229], v[228:229], 0, s[64:65]
	s_mov_b32 m0, s22
	ds_read_b128 v[192:195], v167 offset:49152
	ds_read_b128 v[196:199], v167 offset:50176
	ds_read_b128 v[200:203], v167 offset:51200
	ds_read_b128 v[204:207], v167 offset:52224
	ds_read_b128 v[208:211], v167 offset:53248
	ds_read_b128 v[212:215], v167 offset:54272
	ds_read_b128 v[216:219], v167 offset:55296
	ds_read_b128 v[224:227], v167 offset:56320
	global_load_lds_dwordx4 v[228:229], off
	s_add_i32 m0, s22, 0x2000
	s_add_u32 s8, s8, 0x80080
	v_lshl_add_u64 v[228:229], v[230:231], 0, s[64:65]
	s_addc_u32 s9, s9, 0
	s_add_i32 s22, s48, s30
	global_load_lds_dwordx4 v[228:229], off
	s_mov_b32 m0, s22
	v_lshl_add_u64 v[228:229], s[8:9], 0, v[0:1]
	global_load_lds_dwordx4 v[228:229], off
	s_add_i32 m0, s22, 0x2000
	v_lshl_add_u64 v[228:229], s[8:9], 0, v[126:127]
	global_load_lds_dwordx4 v[228:229], off
	s_mov_b32 m0, s37
	v_lshl_add_u64 v[228:229], v[232:233], 0, s[64:65]
	global_load_lds_dwordx4 v[228:229], off
	s_mov_b32 m0, s76
	v_lshl_add_u64 v[228:229], v[244:245], 0, s[64:65]
	global_load_lds_dwordx4 v[228:229], off
	s_waitcnt vmcnt(8) lgkmcnt(0)
	s_barrier
	v_mfma_f32_16x16x32_bf16 v[62:65], v[156:159], v[192:195], v[62:65]
	v_mfma_f32_16x16x32_bf16 v[58:61], v[168:171], v[192:195], v[58:61]
	v_mfma_f32_16x16x32_bf16 v[46:49], v[156:159], v[200:203], v[46:49]
	v_mfma_f32_16x16x32_bf16 v[42:45], v[168:171], v[200:203], v[42:45]
	v_mfma_f32_16x16x32_bf16 v[30:33], v[156:159], v[208:211], v[30:33]
	v_mfma_f32_16x16x32_bf16 v[26:29], v[168:171], v[208:211], v[26:29]
	v_mfma_f32_16x16x32_bf16 v[14:17], v[156:159], v[216:219], v[14:17]
	v_mfma_f32_16x16x32_bf16 v[10:13], v[168:171], v[216:219], v[10:13]
	v_mfma_f32_16x16x32_bf16 v[62:65], v[160:163], v[196:199], v[62:65]
	v_mfma_f32_16x16x32_bf16 v[58:61], v[172:175], v[196:199], v[58:61]
	v_mfma_f32_16x16x32_bf16 v[46:49], v[160:163], v[204:207], v[46:49]
	v_mfma_f32_16x16x32_bf16 v[42:45], v[172:175], v[204:207], v[42:45]
	v_mfma_f32_16x16x32_bf16 v[30:33], v[160:163], v[212:215], v[30:33]
	v_mfma_f32_16x16x32_bf16 v[26:29], v[172:175], v[212:215], v[26:29]
	v_mfma_f32_16x16x32_bf16 v[14:17], v[160:163], v[224:227], v[14:17]
	v_mfma_f32_16x16x32_bf16 v[10:13], v[172:175], v[224:227], v[10:13]
	v_mfma_f32_16x16x32_bf16 v[54:57], v[176:179], v[192:195], v[54:57]
	v_mfma_f32_16x16x32_bf16 v[50:53], v[184:187], v[192:195], v[50:53]
	v_mfma_f32_16x16x32_bf16 v[38:41], v[176:179], v[200:203], v[38:41]
	v_mfma_f32_16x16x32_bf16 v[34:37], v[184:187], v[200:203], v[34:37]
	v_mfma_f32_16x16x32_bf16 v[22:25], v[176:179], v[208:211], v[22:25]
	v_mfma_f32_16x16x32_bf16 v[18:21], v[184:187], v[208:211], v[18:21]
	v_mfma_f32_16x16x32_bf16 v[6:9], v[176:179], v[216:219], v[6:9]
	v_mfma_f32_16x16x32_bf16 v[2:5], v[184:187], v[216:219], v[2:5]
	v_mfma_f32_16x16x32_bf16 v[54:57], v[180:183], v[196:199], v[54:57]
	v_mfma_f32_16x16x32_bf16 v[50:53], v[188:191], v[196:199], v[50:53]
	v_mfma_f32_16x16x32_bf16 v[38:41], v[180:183], v[204:207], v[38:41]
	v_mfma_f32_16x16x32_bf16 v[34:37], v[188:191], v[204:207], v[34:37]
	v_mfma_f32_16x16x32_bf16 v[22:25], v[180:183], v[212:215], v[22:25]
	v_mfma_f32_16x16x32_bf16 v[18:21], v[188:191], v[212:215], v[18:21]
	v_mfma_f32_16x16x32_bf16 v[6:9], v[180:183], v[224:227], v[6:9]
	v_mfma_f32_16x16x32_bf16 v[2:5], v[188:191], v[224:227], v[2:5]
	s_barrier
	s_add_i32 s42, s42, 2
	s_add_u32 s6, s6, 0x100
	s_addc_u32 s7, s7, 0
	s_add_u32 s40, s40, 0x100
	s_addc_u32 s41, s41, 0
	s_cmp_gt_u32 s42, 29
	s_cbranch_scc0 .LBB0_123
	s_and_b64 vcc, exec, s[12:13]
	s_cbranch_vccz .LBB0_126
	s_barrier

; #define PG8_WAIT_V(n) asm volatile("s_waitcnt vmcnt(" #n ")" ::: "memory")
; #define PG8_BAR __builtin_amdgcn_s_barrier()
; template <class Epi, class Sched, bool ALIGN_EPI = false, bool SP2 = false>
; __device__ __forceinline__ void gemm_phase(PG8_LAS unsigned char* lds, const Gemm g, const Sched& S, const Epi& E) {
;     ...
;     PG8_WAIT_V(0);
;     if constexpr (!ALIGN_EPI) { if (wr == 0) PG8_BAR; }
;     PG8_BAR;
.LBB0_296:
	s_setprio 0
	s_waitcnt vmcnt(0)
	v_readlane_b32 s42, v255, 42
	v_readlane_b32 s43, v255, 43
	v_readlane_b32 s48, v255, 44
	v_readlane_b32 s67, v255, 45
	s_barrier

; #define PG8_STAGE(bufoff, gbase, voff) do { _Pragma("unroll") for (int _i = 0; _i < 2; ++_i) \
;         __builtin_amdgcn_global_load_lds((const unsigned*)((const char*)(gbase) + (voff)[_i]), (PG8_LAS unsigned*)(lds + (bufoff) + ldsw + _i * 8192), 16, 0, 0); } while (0)
; #define PG8_LDA(dst, b, h) do { _Pragma("unroll") for (int m = 0; m < 4; ++m) _Pragma("unroll") for (int k = 0; k < 2; ++k) dst[m][k] = *(const PG8_LAS bf16x8*)(lds + PG8_SA(b, h) + aoff + m * 2048 + k * 1024); } while (0)
; #define PG8_LDB(dst, b, h) do { _Pragma("unroll") for (int n = 0; n < 2; ++n) _Pragma("unroll") for (int k = 0; k < 2; ++k) dst[n][k] = *(const PG8_LAS bf16x8*)(lds + PG8_SB(b, h) + boff + n * 2048 + k * 1024); } while (0)
; #define PG8_MMA(ai, bj, At, Bt) do { __builtin_amdgcn_s_setprio(1); _Pragma("unroll") for (int m = 0; m < 4; ++m) _Pragma("unroll") for (int n = 0; n < 2; ++n) _Pragma("unroll") for (int k = 0; k < 2; ++k) \
;         acc[ai][bj][m][n] = __builtin_amdgcn_mfma_f32_16x16x32_bf16(Bt[n][k], At[m][k], acc[ai][bj][m][n], 0, 0, 0); __builtin_amdgcn_s_setprio(0); } while (0)
; #define PG8_WAIT_V(n) asm volatile("s_waitcnt vmcnt(" #n ")" ::: "memory")
; #define PG8_WAIT_L(n) asm volatile("s_waitcnt lgkmcnt(" #n ")" ::: "memory")
; template <class Epi, class Sched, bool ALIGN_EPI = false, bool SP2 = false>
; __device__ __forceinline__ void gemm_phase(PG8_LAS unsigned char* lds, const Gemm g, const Sched& S, const Epi& E) {
;     ...
;             const bool last = (t == nt - 2);
;             const char* a1 = cA + (size_t)(t + 1) * kstep;
;             const char* a2 = last ? nA : cA + (size_t)(t + 2) * kstep; const char* b2 = last ? nB : cB + (size_t)(t + 2) * kstep;
;             const char* a3 = a2 + kstep; const char* b3 = b2 + kstep;
;             if (last && has_next) S.a_ready(nxt);
;             if constexpr (SP2) {
;             PG8_LDB(B0, 0, 0); PG8_LDB(B1, 0, 1); PG8_SCHED; PG8_LDA(At, 0, 0); PG8_STAGE(PG8_SA(1, 1), a1 + hstep, voffA);
;             PG8_WAIT_V(8); PG8_WAIT_L(0); PG8_BAR; PG8_MMA(0, 0, At, B0); PG8_MMA(0, 1, At, B1); PG8_BAR; PG8_SCHED;
;             PG8_LDA(At, 0, 1); PG8_STAGE(PG8_SB(0, 0), b2, voffB); PG8_STAGE(PG8_SB(0, 1), b2 + hstep, voffB); PG8_STAGE(PG8_SA(0, 0), a2, voffA);
;             PG8_WAIT_V(8); PG8_WAIT_L(0); PG8_BAR; PG8_MMA(1, 0, At, B0); PG8_MMA(1, 1, At, B1); PG8_BAR; PG8_SCHED;
.LBB0_307:
	s_add_u32 s4, s42, s0
	s_addc_u32 s5, s43, s1
	s_add_u32 s4, s4, 0x2cc00100
	s_addc_u32 s5, s5, 0
	s_add_u32 s20, s48, s0
	s_addc_u32 s21, s67, s1
	s_add_i32 s22, 0, 0x10000
	s_cmpk_eq_i32 s0, 0xf00
	s_cselect_b32 s7, s55, s5
	s_cselect_b32 s6, s54, s4
	s_cselect_b32 s5, s53, s21
	s_cselect_b32 s4, s52, s20
	s_add_i32 s23, 0, 0x14000
	v_add_u32_e32 v172, s22, v158
	v_add_u32_e32 v188, s23, v158
	ds_read_b128 v[160:163], v172
	ds_read_b128 v[164:167], v172 offset:1024
	ds_read_b128 v[168:171], v172 offset:2048
	ds_read_b128 v[172:175], v172 offset:3072
	ds_read_b128 v[176:179], v188
	ds_read_b128 v[180:183], v188 offset:1024
	ds_read_b128 v[184:187], v188 offset:2048
	ds_read_b128 v[188:191], v188 offset:3072
	v_lshl_add_u64 v[228:229], v[152:153], 0, s[0:1]
	s_add_i32 m0, s12, 0xc000
	ds_read_b128 v[192:195], v159
	ds_read_b128 v[196:199], v159 offset:1024
	ds_read_b128 v[200:203], v159 offset:2048
	ds_read_b128 v[204:207], v159 offset:3072
	ds_read_b128 v[208:211], v159 offset:4096
	ds_read_b128 v[212:215], v159 offset:5120
	ds_read_b128 v[216:219], v159 offset:6144
	ds_read_b128 v[224:227], v159 offset:7168
	global_load_lds_dwordx4 v[228:229], off
	s_add_i32 m0, s12, 0xe000
	v_lshl_add_u64 v[228:229], v[154:155], 0, s[0:1]
	global_load_lds_dwordx4 v[228:229], off
	s_waitcnt vmcnt(8) lgkmcnt(0)
	s_barrier
	v_mfma_f32_16x16x32_bf16 v[144:147], v[160:163], v[192:195], v[144:147]
	v_mfma_f32_16x16x32_bf16 v[122:125], v[168:171], v[192:195], v[122:125]
	v_mfma_f32_16x16x32_bf16 v[118:121], v[160:163], v[200:203], v[118:121]
	v_mfma_f32_16x16x32_bf16 v[114:117], v[168:171], v[200:203], v[114:117]
	v_mfma_f32_16x16x32_bf16 v[102:105], v[160:163], v[208:211], v[102:105]
	v_mfma_f32_16x16x32_bf16 v[98:101], v[168:171], v[208:211], v[98:101]
	v_mfma_f32_16x16x32_bf16 v[86:89], v[160:163], v[216:219], v[86:89]
	v_mfma_f32_16x16x32_bf16 v[82:85], v[168:171], v[216:219], v[82:85]
	v_mfma_f32_16x16x32_bf16 v[144:147], v[164:167], v[196:199], v[144:147]
	v_mfma_f32_16x16x32_bf16 v[122:125], v[172:175], v[196:199], v[122:125]
	v_mfma_f32_16x16x32_bf16 v[118:121], v[164:167], v[204:207], v[118:121]
	v_mfma_f32_16x16x32_bf16 v[114:117], v[172:175], v[204:207], v[114:117]
	v_mfma_f32_16x16x32_bf16 v[102:105], v[164:167], v[212:215], v[102:105]
	v_mfma_f32_16x16x32_bf16 v[98:101], v[172:175], v[212:215], v[98:101]
	v_mfma_f32_16x16x32_bf16 v[86:89], v[164:167], v[224:227], v[86:89]
	v_mfma_f32_16x16x32_bf16 v[82:85], v[172:175], v[224:227], v[82:85]
	v_mfma_f32_16x16x32_bf16 v[110:113], v[176:179], v[192:195], v[110:113]
	v_mfma_f32_16x16x32_bf16 v[106:109], v[184:187], v[192:195], v[106:109]
	v_mfma_f32_16x16x32_bf16 v[94:97], v[176:179], v[200:203], v[94:97]
	v_mfma_f32_16x16x32_bf16 v[90:93], v[184:187], v[200:203], v[90:93]
	v_mfma_f32_16x16x32_bf16 v[78:81], v[176:179], v[208:211], v[78:81]
	v_mfma_f32_16x16x32_bf16 v[74:77], v[184:187], v[208:211], v[74:77]
	v_mfma_f32_16x16x32_bf16 v[70:73], v[176:179], v[216:219], v[70:73]
	v_mfma_f32_16x16x32_bf16 v[66:69], v[184:187], v[216:219], v[66:69]
	v_mfma_f32_16x16x32_bf16 v[110:113], v[180:183], v[196:199], v[110:113]
	v_mfma_f32_16x16x32_bf16 v[106:109], v[188:191], v[196:199], v[106:109]
	v_mfma_f32_16x16x32_bf16 v[94:97], v[180:183], v[204:207], v[94:97]
	v_mfma_f32_16x16x32_bf16 v[90:93], v[188:191], v[204:207], v[90:93]
	v_mfma_f32_16x16x32_bf16 v[78:81], v[180:183], v[212:215], v[78:81]
	v_mfma_f32_16x16x32_bf16 v[74:77], v[188:191], v[212:215], v[74:77]
	v_mfma_f32_16x16x32_bf16 v[70:73], v[180:183], v[224:227], v[70:73]
	v_mfma_f32_16x16x32_bf16 v[66:69], v[188:191], v[224:227], v[66:69]
	s_barrier
	s_add_i32 s20, s22, s9
	v_lshl_add_u64 v[228:229], s[4:5], 0, v[0:1]
	s_mov_b32 m0, s20
	ds_read_b128 v[192:195], v159 offset:16384
	ds_read_b128 v[196:199], v159 offset:17408
	ds_read_b128 v[200:203], v159 offset:18432
	ds_read_b128 v[204:207], v159 offset:19456
	ds_read_b128 v[208:211], v159 offset:20480
	ds_read_b128 v[212:215], v159 offset:21504
	ds_read_b128 v[216:219], v159 offset:22528
	ds_read_b128 v[224:227], v159 offset:23552
	global_load_lds_dwordx4 v[228:229], off
	s_add_i32 m0, s20, 0x2000
	s_add_u32 s20, s4, 0x80000
	v_lshl_add_u64 v[230:231], s[4:5], 0, v[126:127]
	s_addc_u32 s21, s5, 0
	s_add_i32 s22, s23, s9
	global_load_lds_dwordx4 v[230:231], off
	v_lshl_add_u64 v[232:233], s[20:21], 0, v[0:1]
	s_mov_b32 m0, s22
	v_lshl_add_u64 v[244:245], s[6:7], 0, v[148:149]
	global_load_lds_dwordx4 v[232:233], off
	s_add_i32 m0, s22, 0x2000
	v_lshl_add_u64 v[232:233], s[20:21], 0, v[126:127]
	global_load_lds_dwordx4 v[232:233], off
	s_mov_b32 m0, s12
	v_lshl_add_u64 v[232:233], s[6:7], 0, v[150:151]
	global_load_lds_dwordx4 v[232:233], off
	s_mov_b32 m0, s13
	s_nop 0
	global_load_lds_dwordx4 v[244:245], off
	s_waitcnt vmcnt(8) lgkmcnt(0)
	s_barrier
; #define PG8_STAGE(bufoff, gbase, voff) do { _Pragma("unroll") for (int _i = 0; _i < 2; ++_i) \
;         __builtin_amdgcn_global_load_lds((const unsigned*)((const char*)(gbase) + (voff)[_i]), (PG8_LAS unsigned*)(lds + (bufoff) + ldsw + _i * 8192), 16, 0, 0); } while (0)
; #define PG8_LDA(dst, b, h) do { _Pragma("unroll") for (int m = 0; m < 4; ++m) _Pragma("unroll") for (int k = 0; k < 2; ++k) dst[m][k] = *(const PG8_LAS bf16x8*)(lds + PG8_SA(b, h) + aoff + m * 2048 + k * 1024); } while (0)
; #define PG8_LDB(dst, b, h) do { _Pragma("unroll") for (int n = 0; n < 2; ++n) _Pragma("unroll") for (int k = 0; k < 2; ++k) dst[n][k] = *(const PG8_LAS bf16x8*)(lds + PG8_SB(b, h) + boff + n * 2048 + k * 1024); } while (0)
; #define PG8_MMA(ai, bj, At, Bt) do { __builtin_amdgcn_s_setprio(1); _Pragma("unroll") for (int m = 0; m < 4; ++m) _Pragma("unroll") for (int n = 0; n < 2; ++n) _Pragma("unroll") for (int k = 0; k < 2; ++k) \
;         acc[ai][bj][m][n] = __builtin_amdgcn_mfma_f32_16x16x32_bf16(Bt[n][k], At[m][k], acc[ai][bj][m][n], 0, 0, 0); __builtin_amdgcn_s_setprio(0); } while (0)
; #define PG8_WAIT_V(n) asm volatile("s_waitcnt vmcnt(" #n ")" ::: "memory")
; #define PG8_WAIT_L(n) asm volatile("s_waitcnt lgkmcnt(" #n ")" ::: "memory")
; #define PG8_BAR __builtin_amdgcn_s_barrier()
; #define PG8_SCHED __builtin_amdgcn_sched_barrier(0)
; template <class Epi, class Sched, bool ALIGN_EPI = false, bool SP2 = false>
; __device__ __forceinline__ void gemm_phase(PG8_LAS unsigned char* lds, const Gemm g, const Sched& S, const Epi& E) {
;     ...
;             PG8_WAIT_V(8); PG8_WAIT_L(0); PG8_BAR; PG8_MMA(0, 0, At, B0); PG8_MMA(0, 1, At, B1); PG8_BAR; PG8_SCHED;
;             PG8_LDA(At, 0, 1); PG8_STAGE(PG8_SB(0, 0), b2, voffB); PG8_STAGE(PG8_SB(0, 1), b2 + hstep, voffB); PG8_STAGE(PG8_SA(0, 0), a2, voffA);
;             PG8_WAIT_V(8); PG8_WAIT_L(0); PG8_BAR; PG8_MMA(1, 0, At, B0); PG8_MMA(1, 1, At, B1); PG8_BAR; PG8_SCHED;
;             PG8_LDB(B0, 1, 0); PG8_LDB(B1, 1, 1); PG8_SCHED; PG8_LDA(At, 1, 0); PG8_STAGE(PG8_SA(0, 1), a2 + hstep, voffA);
;             PG8_WAIT_V(8); PG8_WAIT_L(0); PG8_BAR; PG8_MMA(0, 0, At, B0); PG8_MMA(0, 1, At, B1); PG8_BAR; PG8_SCHED;
	v_mfma_f32_16x16x32_bf16 v[62:65], v[160:163], v[192:195], v[62:65]
	v_mfma_f32_16x16x32_bf16 v[58:61], v[168:171], v[192:195], v[58:61]
	v_mfma_f32_16x16x32_bf16 v[54:57], v[160:163], v[200:203], v[54:57]
	v_mfma_f32_16x16x32_bf16 v[50:53], v[168:171], v[200:203], v[50:53]
	v_mfma_f32_16x16x32_bf16 v[38:41], v[160:163], v[208:211], v[38:41]
	v_mfma_f32_16x16x32_bf16 v[34:37], v[168:171], v[208:211], v[34:37]
	v_mfma_f32_16x16x32_bf16 v[22:25], v[160:163], v[216:219], v[22:25]
	v_mfma_f32_16x16x32_bf16 v[18:21], v[168:171], v[216:219], v[18:21]
	v_mfma_f32_16x16x32_bf16 v[62:65], v[164:167], v[196:199], v[62:65]
	v_mfma_f32_16x16x32_bf16 v[58:61], v[172:175], v[196:199], v[58:61]
	v_mfma_f32_16x16x32_bf16 v[54:57], v[164:167], v[204:207], v[54:57]
	v_mfma_f32_16x16x32_bf16 v[50:53], v[172:175], v[204:207], v[50:53]
	v_mfma_f32_16x16x32_bf16 v[38:41], v[164:167], v[212:215], v[38:41]
	v_mfma_f32_16x16x32_bf16 v[34:37], v[172:175], v[212:215], v[34:37]
	v_mfma_f32_16x16x32_bf16 v[22:25], v[164:167], v[224:227], v[22:25]
	v_mfma_f32_16x16x32_bf16 v[18:21], v[172:175], v[224:227], v[18:21]
	v_mfma_f32_16x16x32_bf16 v[46:49], v[176:179], v[192:195], v[46:49]
	v_mfma_f32_16x16x32_bf16 v[42:45], v[184:187], v[192:195], v[42:45]
	v_mfma_f32_16x16x32_bf16 v[30:33], v[176:179], v[200:203], v[30:33]
	v_mfma_f32_16x16x32_bf16 v[26:29], v[184:187], v[200:203], v[26:29]
	v_mfma_f32_16x16x32_bf16 v[14:17], v[176:179], v[208:211], v[14:17]
	v_mfma_f32_16x16x32_bf16 v[10:13], v[184:187], v[208:211], v[10:13]
	v_mfma_f32_16x16x32_bf16 v[6:9], v[176:179], v[216:219], v[6:9]
	v_mfma_f32_16x16x32_bf16 v[2:5], v[184:187], v[216:219], v[2:5]
	v_mfma_f32_16x16x32_bf16 v[46:49], v[180:183], v[196:199], v[46:49]
	v_mfma_f32_16x16x32_bf16 v[42:45], v[188:191], v[196:199], v[42:45]
	v_mfma_f32_16x16x32_bf16 v[30:33], v[180:183], v[204:207], v[30:33]
	v_mfma_f32_16x16x32_bf16 v[26:29], v[188:191], v[204:207], v[26:29]
	v_mfma_f32_16x16x32_bf16 v[14:17], v[180:183], v[212:215], v[14:17]
	v_mfma_f32_16x16x32_bf16 v[10:13], v[188:191], v[212:215], v[10:13]
	v_mfma_f32_16x16x32_bf16 v[6:9], v[180:183], v[224:227], v[6:9]
	v_mfma_f32_16x16x32_bf16 v[2:5], v[188:191], v[224:227], v[2:5]
	s_barrier
	s_add_i32 s20, 0, 0x18000
	s_add_i32 s21, 0, 0x1c000
	v_add_u32_e32 v172, s20, v158
	v_add_u32_e32 v188, s21, v158
	ds_read_b128 v[160:163], v172
	ds_read_b128 v[164:167], v172 offset:1024
	ds_read_b128 v[168:171], v172 offset:2048
	ds_read_b128 v[172:175], v172 offset:3072
	ds_read_b128 v[176:179], v188
	ds_read_b128 v[180:183], v188 offset:1024
	ds_read_b128 v[184:187], v188 offset:2048
	ds_read_b128 v[188:191], v188 offset:3072
	s_add_u32 s6, s6, 0x80000
	s_addc_u32 s7, s7, 0
	s_mov_b32 m0, s14
	v_lshl_add_u64 v[246:247], s[6:7], 0, v[150:151]
	ds_read_b128 v[192:195], v159 offset:32768
	ds_read_b128 v[196:199], v159 offset:33792
	ds_read_b128 v[200:203], v159 offset:34816
	ds_read_b128 v[204:207], v159 offset:35840
	ds_read_b128 v[208:211], v159 offset:36864
	ds_read_b128 v[212:215], v159 offset:37888
	ds_read_b128 v[216:219], v159 offset:38912
	ds_read_b128 v[224:227], v159 offset:39936
	global_load_lds_dwordx4 v[246:247], off
	s_mov_b32 m0, s15
	v_lshl_add_u64 v[246:247], s[6:7], 0, v[148:149]
	global_load_lds_dwordx4 v[246:247], off
	s_waitcnt vmcnt(8) lgkmcnt(0)
	s_barrier
	v_mfma_f32_16x16x32_bf16 v[144:147], v[160:163], v[192:195], v[144:147]
	v_mfma_f32_16x16x32_bf16 v[122:125], v[168:171], v[192:195], v[122:125]
	v_mfma_f32_16x16x32_bf16 v[118:121], v[160:163], v[200:203], v[118:121]
	v_mfma_f32_16x16x32_bf16 v[114:117], v[168:171], v[200:203], v[114:117]
	v_mfma_f32_16x16x32_bf16 v[102:105], v[160:163], v[208:211], v[102:105]
	v_mfma_f32_16x16x32_bf16 v[98:101], v[168:171], v[208:211], v[98:101]
	v_mfma_f32_16x16x32_bf16 v[86:89], v[160:163], v[216:219], v[86:89]
	v_mfma_f32_16x16x32_bf16 v[82:85], v[168:171], v[216:219], v[82:85]
	v_mfma_f32_16x16x32_bf16 v[144:147], v[164:167], v[196:199], v[144:147]
	v_mfma_f32_16x16x32_bf16 v[122:125], v[172:175], v[196:199], v[122:125]
	v_mfma_f32_16x16x32_bf16 v[118:121], v[164:167], v[204:207], v[118:121]
	v_mfma_f32_16x16x32_bf16 v[114:117], v[172:175], v[204:207], v[114:117]
	v_mfma_f32_16x16x32_bf16 v[102:105], v[164:167], v[212:215], v[102:105]
	v_mfma_f32_16x16x32_bf16 v[98:101], v[172:175], v[212:215], v[98:101]
	v_mfma_f32_16x16x32_bf16 v[86:89], v[164:167], v[224:227], v[86:89]
	v_mfma_f32_16x16x32_bf16 v[82:85], v[172:175], v[224:227], v[82:85]
	v_mfma_f32_16x16x32_bf16 v[110:113], v[176:179], v[192:195], v[110:113]
	v_mfma_f32_16x16x32_bf16 v[106:109], v[184:187], v[192:195], v[106:109]
	v_mfma_f32_16x16x32_bf16 v[94:97], v[176:179], v[200:203], v[94:97]
	v_mfma_f32_16x16x32_bf16 v[90:93], v[184:187], v[200:203], v[90:93]
	v_mfma_f32_16x16x32_bf16 v[78:81], v[176:179], v[208:211], v[78:81]
	v_mfma_f32_16x16x32_bf16 v[74:77], v[184:187], v[208:211], v[74:77]
	v_mfma_f32_16x16x32_bf16 v[70:73], v[176:179], v[216:219], v[70:73]
	v_mfma_f32_16x16x32_bf16 v[66:69], v[184:187], v[216:219], v[66:69]
	v_mfma_f32_16x16x32_bf16 v[110:113], v[180:183], v[196:199], v[110:113]
	v_mfma_f32_16x16x32_bf16 v[106:109], v[188:191], v[196:199], v[106:109]
	v_mfma_f32_16x16x32_bf16 v[94:97], v[180:183], v[204:207], v[94:97]
	v_mfma_f32_16x16x32_bf16 v[90:93], v[188:191], v[204:207], v[90:93]
	v_mfma_f32_16x16x32_bf16 v[78:81], v[180:183], v[212:215], v[78:81]
	v_mfma_f32_16x16x32_bf16 v[74:77], v[188:191], v[212:215], v[74:77]
	v_mfma_f32_16x16x32_bf16 v[70:73], v[180:183], v[224:227], v[70:73]
	v_mfma_f32_16x16x32_bf16 v[66:69], v[188:191], v[224:227], v[66:69]
	s_barrier
; #define PG8_STAGE(bufoff, gbase, voff) do { _Pragma("unroll") for (int _i = 0; _i < 2; ++_i) \
;         __builtin_amdgcn_global_load_lds((const unsigned*)((const char*)(gbase) + (voff)[_i]), (PG8_LAS unsigned*)(lds + (bufoff) + ldsw + _i * 8192), 16, 0, 0); } while (0)
; #define PG8_LDA(dst, b, h) do { _Pragma("unroll") for (int m = 0; m < 4; ++m) _Pragma("unroll") for (int k = 0; k < 2; ++k) dst[m][k] = *(const PG8_LAS bf16x8*)(lds + PG8_SA(b, h) + aoff + m * 2048 + k * 1024); } while (0)
; #define PG8_MMA(ai, bj, At, Bt) do { __builtin_amdgcn_s_setprio(1); _Pragma("unroll") for (int m = 0; m < 4; ++m) _Pragma("unroll") for (int n = 0; n < 2; ++n) _Pragma("unroll") for (int k = 0; k < 2; ++k) \
;         acc[ai][bj][m][n] = __builtin_amdgcn_mfma_f32_16x16x32_bf16(Bt[n][k], At[m][k], acc[ai][bj][m][n], 0, 0, 0); __builtin_amdgcn_s_setprio(0); } while (0)
; #define PG8_WAIT_V(n) asm volatile("s_waitcnt vmcnt(" #n ")" ::: "memory")
; #define PG8_WAIT_L(n) asm volatile("s_waitcnt lgkmcnt(" #n ")" ::: "memory")
; #define PG8_BAR __builtin_amdgcn_s_barrier()
; #define PG8_SCHED __builtin_amdgcn_sched_barrier(0)
; template <class Epi, class Sched, bool ALIGN_EPI = false, bool SP2 = false>
; __device__ __forceinline__ void gemm_phase(PG8_LAS unsigned char* lds, const Gemm g, const Sched& S, const Epi& E) {
;     ...
;         for (int t = 0; t < nt; t += 2) {
;     ...
;             PG8_WAIT_V(8); PG8_WAIT_L(0); PG8_BAR; PG8_MMA(0, 0, At, B0); PG8_MMA(0, 1, At, B1); PG8_BAR; PG8_SCHED;
;             PG8_LDA(At, 1, 1); PG8_STAGE(PG8_SB(1, 0), b3, voffB); PG8_STAGE(PG8_SB(1, 1), b3 + hstep, voffB); PG8_STAGE(PG8_SA(1, 0), a3, voffA);
;             PG8_WAIT_V(8); PG8_WAIT_L(0); PG8_BAR; PG8_MMA(1, 0, At, B0); PG8_MMA(1, 1, At, B1); PG8_BAR; PG8_SCHED;
	s_add_i32 s6, s20, s9
	v_lshl_add_u64 v[228:229], v[228:229], 0, s[64:65]
	s_mov_b32 m0, s6
	ds_read_b128 v[192:195], v159 offset:49152
	ds_read_b128 v[196:199], v159 offset:50176
	ds_read_b128 v[200:203], v159 offset:51200
	ds_read_b128 v[204:207], v159 offset:52224
	ds_read_b128 v[208:211], v159 offset:53248
	ds_read_b128 v[212:215], v159 offset:54272
	ds_read_b128 v[216:219], v159 offset:55296
	ds_read_b128 v[224:227], v159 offset:56320
	global_load_lds_dwordx4 v[228:229], off
	s_add_i32 m0, s6, 0x2000
	s_add_u32 s4, s4, 0x80080
	v_lshl_add_u64 v[228:229], v[230:231], 0, s[64:65]
	s_addc_u32 s5, s5, 0
	s_add_i32 s6, s21, s9
	global_load_lds_dwordx4 v[228:229], off
	s_mov_b32 m0, s6
	v_lshl_add_u64 v[228:229], s[4:5], 0, v[0:1]
	global_load_lds_dwordx4 v[228:229], off
	s_add_i32 m0, s6, 0x2000
	v_lshl_add_u64 v[228:229], s[4:5], 0, v[126:127]
	global_load_lds_dwordx4 v[228:229], off
	s_mov_b32 m0, s17
	v_lshl_add_u64 v[228:229], v[232:233], 0, s[64:65]
	global_load_lds_dwordx4 v[228:229], off
	s_mov_b32 m0, s18
	v_lshl_add_u64 v[228:229], v[244:245], 0, s[64:65]
	global_load_lds_dwordx4 v[228:229], off
	s_waitcnt vmcnt(8) lgkmcnt(0)
	s_barrier
	v_mfma_f32_16x16x32_bf16 v[62:65], v[160:163], v[192:195], v[62:65]
	v_mfma_f32_16x16x32_bf16 v[58:61], v[168:171], v[192:195], v[58:61]
	v_mfma_f32_16x16x32_bf16 v[54:57], v[160:163], v[200:203], v[54:57]
	v_mfma_f32_16x16x32_bf16 v[50:53], v[168:171], v[200:203], v[50:53]
	v_mfma_f32_16x16x32_bf16 v[38:41], v[160:163], v[208:211], v[38:41]
	v_mfma_f32_16x16x32_bf16 v[34:37], v[168:171], v[208:211], v[34:37]
	v_mfma_f32_16x16x32_bf16 v[22:25], v[160:163], v[216:219], v[22:25]
	v_mfma_f32_16x16x32_bf16 v[18:21], v[168:171], v[216:219], v[18:21]
	v_mfma_f32_16x16x32_bf16 v[62:65], v[164:167], v[196:199], v[62:65]
	v_mfma_f32_16x16x32_bf16 v[58:61], v[172:175], v[196:199], v[58:61]
	v_mfma_f32_16x16x32_bf16 v[54:57], v[164:167], v[204:207], v[54:57]
	v_mfma_f32_16x16x32_bf16 v[50:53], v[172:175], v[204:207], v[50:53]
	v_mfma_f32_16x16x32_bf16 v[38:41], v[164:167], v[212:215], v[38:41]
	v_mfma_f32_16x16x32_bf16 v[34:37], v[172:175], v[212:215], v[34:37]
	v_mfma_f32_16x16x32_bf16 v[22:25], v[164:167], v[224:227], v[22:25]
	v_mfma_f32_16x16x32_bf16 v[18:21], v[172:175], v[224:227], v[18:21]
	v_mfma_f32_16x16x32_bf16 v[46:49], v[176:179], v[192:195], v[46:49]
	v_mfma_f32_16x16x32_bf16 v[42:45], v[184:187], v[192:195], v[42:45]
	v_mfma_f32_16x16x32_bf16 v[30:33], v[176:179], v[200:203], v[30:33]
	v_mfma_f32_16x16x32_bf16 v[26:29], v[184:187], v[200:203], v[26:29]
	v_mfma_f32_16x16x32_bf16 v[14:17], v[176:179], v[208:211], v[14:17]
	v_mfma_f32_16x16x32_bf16 v[10:13], v[184:187], v[208:211], v[10:13]
	v_mfma_f32_16x16x32_bf16 v[6:9], v[176:179], v[216:219], v[6:9]
	v_mfma_f32_16x16x32_bf16 v[2:5], v[184:187], v[216:219], v[2:5]
	v_mfma_f32_16x16x32_bf16 v[46:49], v[180:183], v[196:199], v[46:49]
	v_mfma_f32_16x16x32_bf16 v[42:45], v[188:191], v[196:199], v[42:45]
	v_mfma_f32_16x16x32_bf16 v[30:33], v[180:183], v[204:207], v[30:33]
	v_mfma_f32_16x16x32_bf16 v[26:29], v[188:191], v[204:207], v[26:29]
	v_mfma_f32_16x16x32_bf16 v[14:17], v[180:183], v[212:215], v[14:17]
	v_mfma_f32_16x16x32_bf16 v[10:13], v[188:191], v[212:215], v[10:13]
	v_mfma_f32_16x16x32_bf16 v[6:9], v[180:183], v[224:227], v[6:9]
	v_mfma_f32_16x16x32_bf16 v[2:5], v[188:191], v[224:227], v[2:5]
	s_barrier
	s_add_i32 s19, s19, 2
	s_add_u32 s0, s0, 0x100
	s_addc_u32 s1, s1, 0
	s_cmp_gt_u32 s19, 29
	s_cbranch_scc0 .LBB0_307
	s_cmpk_lt_u32 s8, 0x100
	s_cbranch_scc0 .LBB0_310
	s_barrier

; #define PG8_STAGE(bufoff, gbase, voff) do { _Pragma("unroll") for (int _i = 0; _i < 2; ++_i) \
;         __builtin_amdgcn_global_load_lds((const unsigned*)((const char*)(gbase) + (voff)[_i]), (PG8_LAS unsigned*)(lds + (bufoff) + ldsw + _i * 8192), 16, 0, 0); } while (0)
; #define PG8_LDA(dst, b, h) do { _Pragma("unroll") for (int m = 0; m < 4; ++m) _Pragma("unroll") for (int k = 0; k < 2; ++k) dst[m][k] = *(const PG8_LAS bf16x8*)(lds + PG8_SA(b, h) + aoff + m * 2048 + k * 1024); } while (0)
; #define PG8_LDB(dst, b, h) do { _Pragma("unroll") for (int n = 0; n < 2; ++n) _Pragma("unroll") for (int k = 0; k < 2; ++k) dst[n][k] = *(const PG8_LAS bf16x8*)(lds + PG8_SB(b, h) + boff + n * 2048 + k * 1024); } while (0)
; #define PG8_MMA(ai, bj, At, Bt) do { __builtin_amdgcn_s_setprio(1); _Pragma("unroll") for (int m = 0; m < 4; ++m) _Pragma("unroll") for (int n = 0; n < 2; ++n) _Pragma("unroll") for (int k = 0; k < 2; ++k) \
;         acc[ai][bj][m][n] = __builtin_amdgcn_mfma_f32_16x16x32_bf16(Bt[n][k], At[m][k], acc[ai][bj][m][n], 0, 0, 0); __builtin_amdgcn_s_setprio(0); } while (0)
; #define PG8_WAIT_V(n) asm volatile("s_waitcnt vmcnt(" #n ")" ::: "memory")
; #define PG8_WAIT_L(n) asm volatile("s_waitcnt lgkmcnt(" #n ")" ::: "memory")
; #define PG8_BAR __builtin_amdgcn_s_barrier()
; template <class Epi, class Sched, bool ALIGN_EPI = false, bool SP2 = false>
; __device__ __forceinline__ void gemm_phase(PG8_LAS unsigned char* lds, const Gemm g, const Sched& S, const Epi& E) {
;     ...
;             const char* a1 = cA + (size_t)(t + 1) * kstep;
;             const char* a2 = last ? nA : cA + (size_t)(t + 2) * kstep; const char* b2 = last ? nB : cB + (size_t)(t + 2) * kstep;
;             const char* a3 = a2 + kstep; const char* b3 = b2 + kstep;
;             if (last && has_next) S.a_ready(nxt);
;             if constexpr (SP2) {
;             PG8_LDB(B0, 0, 0); PG8_LDB(B1, 0, 1); PG8_SCHED; PG8_LDA(At, 0, 0); PG8_STAGE(PG8_SA(1, 1), a1 + hstep, voffA);
;             PG8_WAIT_V(8); PG8_WAIT_L(0); PG8_BAR; PG8_MMA(0, 0, At, B0); PG8_MMA(0, 1, At, B1); PG8_BAR; PG8_SCHED;
;             PG8_LDA(At, 0, 1); PG8_STAGE(PG8_SB(0, 0), b2, voffB); PG8_STAGE(PG8_SB(0, 1), b2 + hstep, voffB); PG8_STAGE(PG8_SA(0, 0), a2, voffA);
;             PG8_WAIT_V(8); PG8_WAIT_L(0); PG8_BAR; PG8_MMA(1, 0, At, B0); PG8_MMA(1, 1, At, B1); PG8_BAR; PG8_SCHED;
.LBB0_733:
	s_add_u32 s22, s18, s20
	s_addc_u32 s23, s19, s21
	s_add_u32 s22, s22, 0x100
	s_addc_u32 s23, s23, 0
	s_add_u32 s26, s86, s20
	s_addc_u32 s27, s87, s21
	s_add_i32 s40, 0, 0x10000
	s_cmpk_eq_i32 s20, 0xf00
	s_cselect_b32 s25, s13, s23
	s_cselect_b32 s24, s82, s22
	s_cselect_b32 s23, s9, s27
	s_cselect_b32 s22, s83, s26
	s_add_i32 s41, 0, 0x14000
	v_add_u32_e32 v160, s40, v245
	v_add_u32_e32 v176, s41, v245
	ds_read_b128 v[148:151], v160
	ds_read_b128 v[152:155], v160 offset:1024
	ds_read_b128 v[156:159], v160 offset:2048
	ds_read_b128 v[160:163], v160 offset:3072
	ds_read_b128 v[164:167], v176
	ds_read_b128 v[168:171], v176 offset:1024
	ds_read_b128 v[172:175], v176 offset:2048
	ds_read_b128 v[176:179], v176 offset:3072
	v_lshl_add_u64 v[232:233], v[228:229], 0, s[20:21]
	s_add_i32 m0, s31, 0xc000
	ds_read_b128 v[180:183], v247
	ds_read_b128 v[184:187], v247 offset:1024
	ds_read_b128 v[188:191], v247 offset:2048
	ds_read_b128 v[192:195], v247 offset:3072
	ds_read_b128 v[196:199], v247 offset:4096
	ds_read_b128 v[200:203], v247 offset:5120
	ds_read_b128 v[204:207], v247 offset:6144
	ds_read_b128 v[208:211], v247 offset:7168
	global_load_lds_dwordx4 v[232:233], off
	s_add_i32 m0, s31, 0xe000
	v_lshl_add_u64 v[232:233], v[230:231], 0, s[20:21]
	global_load_lds_dwordx4 v[232:233], off
	s_waitcnt vmcnt(8) lgkmcnt(0)
	s_barrier
	v_mfma_f32_16x16x32_bf16 v[144:147], v[148:151], v[180:183], v[144:147]
	v_mfma_f32_16x16x32_bf16 v[122:125], v[156:159], v[180:183], v[122:125]
	v_mfma_f32_16x16x32_bf16 v[110:113], v[148:151], v[188:191], v[110:113]
	v_mfma_f32_16x16x32_bf16 v[106:109], v[156:159], v[188:191], v[106:109]
	v_mfma_f32_16x16x32_bf16 v[94:97], v[148:151], v[196:199], v[94:97]
	v_mfma_f32_16x16x32_bf16 v[90:93], v[156:159], v[196:199], v[90:93]
	v_mfma_f32_16x16x32_bf16 v[78:81], v[148:151], v[204:207], v[78:81]
	v_mfma_f32_16x16x32_bf16 v[74:77], v[156:159], v[204:207], v[74:77]
	v_mfma_f32_16x16x32_bf16 v[144:147], v[152:155], v[184:187], v[144:147]
	v_mfma_f32_16x16x32_bf16 v[122:125], v[160:163], v[184:187], v[122:125]
	v_mfma_f32_16x16x32_bf16 v[110:113], v[152:155], v[192:195], v[110:113]
	v_mfma_f32_16x16x32_bf16 v[106:109], v[160:163], v[192:195], v[106:109]
	v_mfma_f32_16x16x32_bf16 v[94:97], v[152:155], v[200:203], v[94:97]
	v_mfma_f32_16x16x32_bf16 v[90:93], v[160:163], v[200:203], v[90:93]
	v_mfma_f32_16x16x32_bf16 v[78:81], v[152:155], v[208:211], v[78:81]
	v_mfma_f32_16x16x32_bf16 v[74:77], v[160:163], v[208:211], v[74:77]
	v_mfma_f32_16x16x32_bf16 v[118:121], v[164:167], v[180:183], v[118:121]
	v_mfma_f32_16x16x32_bf16 v[114:117], v[172:175], v[180:183], v[114:117]
	v_mfma_f32_16x16x32_bf16 v[102:105], v[164:167], v[188:191], v[102:105]
	v_mfma_f32_16x16x32_bf16 v[98:101], v[172:175], v[188:191], v[98:101]
	v_mfma_f32_16x16x32_bf16 v[86:89], v[164:167], v[196:199], v[86:89]
	v_mfma_f32_16x16x32_bf16 v[82:85], v[172:175], v[196:199], v[82:85]
	v_mfma_f32_16x16x32_bf16 v[70:73], v[164:167], v[204:207], v[70:73]
	v_mfma_f32_16x16x32_bf16 v[66:69], v[172:175], v[204:207], v[66:69]
	v_mfma_f32_16x16x32_bf16 v[118:121], v[168:171], v[184:187], v[118:121]
	v_mfma_f32_16x16x32_bf16 v[114:117], v[176:179], v[184:187], v[114:117]
	v_mfma_f32_16x16x32_bf16 v[102:105], v[168:171], v[192:195], v[102:105]
	v_mfma_f32_16x16x32_bf16 v[98:101], v[176:179], v[192:195], v[98:101]
	v_mfma_f32_16x16x32_bf16 v[86:89], v[168:171], v[200:203], v[86:89]
	v_mfma_f32_16x16x32_bf16 v[82:85], v[176:179], v[200:203], v[82:85]
	v_mfma_f32_16x16x32_bf16 v[70:73], v[168:171], v[208:211], v[70:73]
	v_mfma_f32_16x16x32_bf16 v[66:69], v[176:179], v[208:211], v[66:69]
	s_barrier
	s_add_i32 s26, s40, s30
	v_lshl_add_u64 v[232:233], s[22:23], 0, v[0:1]
	s_mov_b32 m0, s26
	ds_read_b128 v[180:183], v247 offset:16384
	ds_read_b128 v[184:187], v247 offset:17408
	ds_read_b128 v[188:191], v247 offset:18432
	ds_read_b128 v[192:195], v247 offset:19456
	ds_read_b128 v[196:199], v247 offset:20480
	ds_read_b128 v[200:203], v247 offset:21504
	ds_read_b128 v[204:207], v247 offset:22528
	ds_read_b128 v[208:211], v247 offset:23552
	global_load_lds_dwordx4 v[232:233], off
	s_add_i32 m0, s26, 0x2000
	s_add_u32 s26, s22, 0x80000
	v_lshl_add_u64 v[248:249], s[22:23], 0, v[126:127]
	s_addc_u32 s27, s23, 0
	s_add_i32 s40, s41, s30
	global_load_lds_dwordx4 v[248:249], off
	v_lshl_add_u64 v[250:251], s[26:27], 0, v[0:1]
	s_mov_b32 m0, s40
	v_lshl_add_u64 v[220:221], s[24:25], 0, v[212:213]
	global_load_lds_dwordx4 v[250:251], off
	s_add_i32 m0, s40, 0x2000
	v_lshl_add_u64 v[250:251], s[26:27], 0, v[126:127]
	global_load_lds_dwordx4 v[250:251], off
	s_mov_b32 m0, s31
	v_lshl_add_u64 v[250:251], s[24:25], 0, v[214:215]
	global_load_lds_dwordx4 v[250:251], off
	s_mov_b32 m0, s34
	s_nop 0
	global_load_lds_dwordx4 v[220:221], off
	s_waitcnt vmcnt(8) lgkmcnt(0)
	s_barrier
; #define PG8_STAGE(bufoff, gbase, voff) do { _Pragma("unroll") for (int _i = 0; _i < 2; ++_i) \
;         __builtin_amdgcn_global_load_lds((const unsigned*)((const char*)(gbase) + (voff)[_i]), (PG8_LAS unsigned*)(lds + (bufoff) + ldsw + _i * 8192), 16, 0, 0); } while (0)
; #define PG8_LDA(dst, b, h) do { _Pragma("unroll") for (int m = 0; m < 4; ++m) _Pragma("unroll") for (int k = 0; k < 2; ++k) dst[m][k] = *(const PG8_LAS bf16x8*)(lds + PG8_SA(b, h) + aoff + m * 2048 + k * 1024); } while (0)
; #define PG8_LDB(dst, b, h) do { _Pragma("unroll") for (int n = 0; n < 2; ++n) _Pragma("unroll") for (int k = 0; k < 2; ++k) dst[n][k] = *(const PG8_LAS bf16x8*)(lds + PG8_SB(b, h) + boff + n * 2048 + k * 1024); } while (0)
; #define PG8_MMA(ai, bj, At, Bt) do { __builtin_amdgcn_s_setprio(1); _Pragma("unroll") for (int m = 0; m < 4; ++m) _Pragma("unroll") for (int n = 0; n < 2; ++n) _Pragma("unroll") for (int k = 0; k < 2; ++k) \
;         acc[ai][bj][m][n] = __builtin_amdgcn_mfma_f32_16x16x32_bf16(Bt[n][k], At[m][k], acc[ai][bj][m][n], 0, 0, 0); __builtin_amdgcn_s_setprio(0); } while (0)
; #define PG8_WAIT_V(n) asm volatile("s_waitcnt vmcnt(" #n ")" ::: "memory")
; #define PG8_WAIT_L(n) asm volatile("s_waitcnt lgkmcnt(" #n ")" ::: "memory")
; #define PG8_BAR __builtin_amdgcn_s_barrier()
; #define PG8_SCHED __builtin_amdgcn_sched_barrier(0)
; template <class Epi, class Sched, bool ALIGN_EPI = false, bool SP2 = false>
; __device__ __forceinline__ void gemm_phase(PG8_LAS unsigned char* lds, const Gemm g, const Sched& S, const Epi& E) {
;     ...
;             PG8_WAIT_V(8); PG8_WAIT_L(0); PG8_BAR; PG8_MMA(0, 0, At, B0); PG8_MMA(0, 1, At, B1); PG8_BAR; PG8_SCHED;
;             PG8_LDA(At, 0, 1); PG8_STAGE(PG8_SB(0, 0), b2, voffB); PG8_STAGE(PG8_SB(0, 1), b2 + hstep, voffB); PG8_STAGE(PG8_SA(0, 0), a2, voffA);
;             PG8_WAIT_V(8); PG8_WAIT_L(0); PG8_BAR; PG8_MMA(1, 0, At, B0); PG8_MMA(1, 1, At, B1); PG8_BAR; PG8_SCHED;
;             PG8_LDB(B0, 1, 0); PG8_LDB(B1, 1, 1); PG8_SCHED; PG8_LDA(At, 1, 0); PG8_STAGE(PG8_SA(0, 1), a2 + hstep, voffA);
;             PG8_WAIT_V(8); PG8_WAIT_L(0); PG8_BAR; PG8_MMA(0, 0, At, B0); PG8_MMA(0, 1, At, B1); PG8_BAR; PG8_SCHED;
	v_mfma_f32_16x16x32_bf16 v[62:65], v[148:151], v[180:183], v[62:65]
	v_mfma_f32_16x16x32_bf16 v[58:61], v[156:159], v[180:183], v[58:61]
	v_mfma_f32_16x16x32_bf16 v[46:49], v[148:151], v[188:191], v[46:49]
	v_mfma_f32_16x16x32_bf16 v[42:45], v[156:159], v[188:191], v[42:45]
	v_mfma_f32_16x16x32_bf16 v[30:33], v[148:151], v[196:199], v[30:33]
	v_mfma_f32_16x16x32_bf16 v[26:29], v[156:159], v[196:199], v[26:29]
	v_mfma_f32_16x16x32_bf16 v[14:17], v[148:151], v[204:207], v[14:17]
	v_mfma_f32_16x16x32_bf16 v[10:13], v[156:159], v[204:207], v[10:13]
	v_mfma_f32_16x16x32_bf16 v[62:65], v[152:155], v[184:187], v[62:65]
	v_mfma_f32_16x16x32_bf16 v[58:61], v[160:163], v[184:187], v[58:61]
	v_mfma_f32_16x16x32_bf16 v[46:49], v[152:155], v[192:195], v[46:49]
	v_mfma_f32_16x16x32_bf16 v[42:45], v[160:163], v[192:195], v[42:45]
	v_mfma_f32_16x16x32_bf16 v[30:33], v[152:155], v[200:203], v[30:33]
	v_mfma_f32_16x16x32_bf16 v[26:29], v[160:163], v[200:203], v[26:29]
	v_mfma_f32_16x16x32_bf16 v[14:17], v[152:155], v[208:211], v[14:17]
	v_mfma_f32_16x16x32_bf16 v[10:13], v[160:163], v[208:211], v[10:13]
	v_mfma_f32_16x16x32_bf16 v[54:57], v[164:167], v[180:183], v[54:57]
	v_mfma_f32_16x16x32_bf16 v[50:53], v[172:175], v[180:183], v[50:53]
	v_mfma_f32_16x16x32_bf16 v[38:41], v[164:167], v[188:191], v[38:41]
	v_mfma_f32_16x16x32_bf16 v[34:37], v[172:175], v[188:191], v[34:37]
	v_mfma_f32_16x16x32_bf16 v[22:25], v[164:167], v[196:199], v[22:25]
	v_mfma_f32_16x16x32_bf16 v[18:21], v[172:175], v[196:199], v[18:21]
	v_mfma_f32_16x16x32_bf16 v[6:9], v[164:167], v[204:207], v[6:9]
	v_mfma_f32_16x16x32_bf16 v[2:5], v[172:175], v[204:207], v[2:5]
	v_mfma_f32_16x16x32_bf16 v[54:57], v[168:171], v[184:187], v[54:57]
	v_mfma_f32_16x16x32_bf16 v[50:53], v[176:179], v[184:187], v[50:53]
	v_mfma_f32_16x16x32_bf16 v[38:41], v[168:171], v[192:195], v[38:41]
	v_mfma_f32_16x16x32_bf16 v[34:37], v[176:179], v[192:195], v[34:37]
	v_mfma_f32_16x16x32_bf16 v[22:25], v[168:171], v[200:203], v[22:25]
	v_mfma_f32_16x16x32_bf16 v[18:21], v[176:179], v[200:203], v[18:21]
	v_mfma_f32_16x16x32_bf16 v[6:9], v[168:171], v[208:211], v[6:9]
	v_mfma_f32_16x16x32_bf16 v[2:5], v[176:179], v[208:211], v[2:5]
	s_barrier
	s_add_i32 s26, 0, 0x18000
	s_add_i32 s27, 0, 0x1c000
	v_add_u32_e32 v160, s26, v245
	v_add_u32_e32 v176, s27, v245
	ds_read_b128 v[148:151], v160
	ds_read_b128 v[152:155], v160 offset:1024
	ds_read_b128 v[156:159], v160 offset:2048
	ds_read_b128 v[160:163], v160 offset:3072
	ds_read_b128 v[164:167], v176
	ds_read_b128 v[168:171], v176 offset:1024
	ds_read_b128 v[172:175], v176 offset:2048
	ds_read_b128 v[176:179], v176 offset:3072
	s_add_u32 s24, s24, 0x80000
	s_addc_u32 s25, s25, 0
	s_mov_b32 m0, s35
	v_lshl_add_u64 v[222:223], s[24:25], 0, v[214:215]
	ds_read_b128 v[180:183], v247 offset:32768
	ds_read_b128 v[184:187], v247 offset:33792
	ds_read_b128 v[188:191], v247 offset:34816
	ds_read_b128 v[192:195], v247 offset:35840
	ds_read_b128 v[196:199], v247 offset:36864
	ds_read_b128 v[200:203], v247 offset:37888
	ds_read_b128 v[204:207], v247 offset:38912
	ds_read_b128 v[208:211], v247 offset:39936
	global_load_lds_dwordx4 v[222:223], off
	s_mov_b32 m0, s36
	v_lshl_add_u64 v[222:223], s[24:25], 0, v[212:213]
	global_load_lds_dwordx4 v[222:223], off
	s_waitcnt vmcnt(8) lgkmcnt(0)
	s_barrier
	v_mfma_f32_16x16x32_bf16 v[144:147], v[148:151], v[180:183], v[144:147]
	v_mfma_f32_16x16x32_bf16 v[122:125], v[156:159], v[180:183], v[122:125]
	v_mfma_f32_16x16x32_bf16 v[110:113], v[148:151], v[188:191], v[110:113]
	v_mfma_f32_16x16x32_bf16 v[106:109], v[156:159], v[188:191], v[106:109]
	v_mfma_f32_16x16x32_bf16 v[94:97], v[148:151], v[196:199], v[94:97]
	v_mfma_f32_16x16x32_bf16 v[90:93], v[156:159], v[196:199], v[90:93]
	v_mfma_f32_16x16x32_bf16 v[78:81], v[148:151], v[204:207], v[78:81]
	v_mfma_f32_16x16x32_bf16 v[74:77], v[156:159], v[204:207], v[74:77]
	v_mfma_f32_16x16x32_bf16 v[144:147], v[152:155], v[184:187], v[144:147]
	v_mfma_f32_16x16x32_bf16 v[122:125], v[160:163], v[184:187], v[122:125]
	v_mfma_f32_16x16x32_bf16 v[110:113], v[152:155], v[192:195], v[110:113]
	v_mfma_f32_16x16x32_bf16 v[106:109], v[160:163], v[192:195], v[106:109]
	v_mfma_f32_16x16x32_bf16 v[94:97], v[152:155], v[200:203], v[94:97]
	v_mfma_f32_16x16x32_bf16 v[90:93], v[160:163], v[200:203], v[90:93]
	v_mfma_f32_16x16x32_bf16 v[78:81], v[152:155], v[208:211], v[78:81]
	v_mfma_f32_16x16x32_bf16 v[74:77], v[160:163], v[208:211], v[74:77]
	v_mfma_f32_16x16x32_bf16 v[118:121], v[164:167], v[180:183], v[118:121]
	v_mfma_f32_16x16x32_bf16 v[114:117], v[172:175], v[180:183], v[114:117]
	v_mfma_f32_16x16x32_bf16 v[102:105], v[164:167], v[188:191], v[102:105]
	v_mfma_f32_16x16x32_bf16 v[98:101], v[172:175], v[188:191], v[98:101]
	v_mfma_f32_16x16x32_bf16 v[86:89], v[164:167], v[196:199], v[86:89]
	v_mfma_f32_16x16x32_bf16 v[82:85], v[172:175], v[196:199], v[82:85]
	v_mfma_f32_16x16x32_bf16 v[70:73], v[164:167], v[204:207], v[70:73]
	v_mfma_f32_16x16x32_bf16 v[66:69], v[172:175], v[204:207], v[66:69]
	v_mfma_f32_16x16x32_bf16 v[118:121], v[168:171], v[184:187], v[118:121]
	v_mfma_f32_16x16x32_bf16 v[114:117], v[176:179], v[184:187], v[114:117]
	v_mfma_f32_16x16x32_bf16 v[102:105], v[168:171], v[192:195], v[102:105]
	v_mfma_f32_16x16x32_bf16 v[98:101], v[176:179], v[192:195], v[98:101]
	v_mfma_f32_16x16x32_bf16 v[86:89], v[168:171], v[200:203], v[86:89]
	v_mfma_f32_16x16x32_bf16 v[82:85], v[176:179], v[200:203], v[82:85]
	v_mfma_f32_16x16x32_bf16 v[70:73], v[168:171], v[208:211], v[70:73]
	v_mfma_f32_16x16x32_bf16 v[66:69], v[176:179], v[208:211], v[66:69]
	s_barrier
; #define PG8_STAGE(bufoff, gbase, voff) do { _Pragma("unroll") for (int _i = 0; _i < 2; ++_i) \
;         __builtin_amdgcn_global_load_lds((const unsigned*)((const char*)(gbase) + (voff)[_i]), (PG8_LAS unsigned*)(lds + (bufoff) + ldsw + _i * 8192), 16, 0, 0); } while (0)
; #define PG8_LDA(dst, b, h) do { _Pragma("unroll") for (int m = 0; m < 4; ++m) _Pragma("unroll") for (int k = 0; k < 2; ++k) dst[m][k] = *(const PG8_LAS bf16x8*)(lds + PG8_SA(b, h) + aoff + m * 2048 + k * 1024); } while (0)
; #define PG8_MMA(ai, bj, At, Bt) do { __builtin_amdgcn_s_setprio(1); _Pragma("unroll") for (int m = 0; m < 4; ++m) _Pragma("unroll") for (int n = 0; n < 2; ++n) _Pragma("unroll") for (int k = 0; k < 2; ++k) \
;         acc[ai][bj][m][n] = __builtin_amdgcn_mfma_f32_16x16x32_bf16(Bt[n][k], At[m][k], acc[ai][bj][m][n], 0, 0, 0); __builtin_amdgcn_s_setprio(0); } while (0)
; #define PG8_WAIT_V(n) asm volatile("s_waitcnt vmcnt(" #n ")" ::: "memory")
; #define PG8_WAIT_L(n) asm volatile("s_waitcnt lgkmcnt(" #n ")" ::: "memory")
; #define PG8_BAR __builtin_amdgcn_s_barrier()
; #define PG8_SCHED __builtin_amdgcn_sched_barrier(0)
; template <class Epi, class Sched, bool ALIGN_EPI = false, bool SP2 = false>
; __device__ __forceinline__ void gemm_phase(PG8_LAS unsigned char* lds, const Gemm g, const Sched& S, const Epi& E) {
;     ...
;         for (int t = 0; t < nt; t += 2) {
;     ...
;             PG8_WAIT_V(8); PG8_WAIT_L(0); PG8_BAR; PG8_MMA(0, 0, At, B0); PG8_MMA(0, 1, At, B1); PG8_BAR; PG8_SCHED;
;             PG8_LDA(At, 1, 1); PG8_STAGE(PG8_SB(1, 0), b3, voffB); PG8_STAGE(PG8_SB(1, 1), b3 + hstep, voffB); PG8_STAGE(PG8_SA(1, 0), a3, voffA);
;             PG8_WAIT_V(8); PG8_WAIT_L(0); PG8_BAR; PG8_MMA(1, 0, At, B0); PG8_MMA(1, 1, At, B1); PG8_BAR; PG8_SCHED;
	s_add_i32 s24, s26, s30
	v_lshl_add_u64 v[222:223], v[232:233], 0, s[64:65]
	s_mov_b32 m0, s24
	ds_read_b128 v[180:183], v247 offset:49152
	ds_read_b128 v[184:187], v247 offset:50176
	ds_read_b128 v[188:191], v247 offset:51200
	ds_read_b128 v[192:195], v247 offset:52224
	ds_read_b128 v[196:199], v247 offset:53248
	ds_read_b128 v[200:203], v247 offset:54272
	ds_read_b128 v[204:207], v247 offset:55296
	ds_read_b128 v[208:211], v247 offset:56320
	global_load_lds_dwordx4 v[222:223], off
	s_add_i32 m0, s24, 0x2000
	s_add_u32 s22, s22, 0x80080
	v_lshl_add_u64 v[222:223], v[248:249], 0, s[64:65]
	s_addc_u32 s23, s23, 0
	s_add_i32 s24, s27, s30
	global_load_lds_dwordx4 v[222:223], off
	v_lshl_add_u64 v[222:223], s[22:23], 0, v[0:1]
	s_mov_b32 m0, s24
	v_lshl_add_u64 v[220:221], v[220:221], 0, s[64:65]
	global_load_lds_dwordx4 v[222:223], off
	s_add_i32 m0, s24, 0x2000
	v_lshl_add_u64 v[222:223], s[22:23], 0, v[126:127]
	global_load_lds_dwordx4 v[222:223], off
	s_mov_b32 m0, s37
	v_lshl_add_u64 v[222:223], v[250:251], 0, s[64:65]
	global_load_lds_dwordx4 v[222:223], off
	s_mov_b32 m0, s84
	s_nop 0
	global_load_lds_dwordx4 v[220:221], off
	s_waitcnt vmcnt(8) lgkmcnt(0)
	s_barrier
	v_mfma_f32_16x16x32_bf16 v[62:65], v[148:151], v[180:183], v[62:65]
	v_mfma_f32_16x16x32_bf16 v[58:61], v[156:159], v[180:183], v[58:61]
	v_mfma_f32_16x16x32_bf16 v[46:49], v[148:151], v[188:191], v[46:49]
	v_mfma_f32_16x16x32_bf16 v[42:45], v[156:159], v[188:191], v[42:45]
	v_mfma_f32_16x16x32_bf16 v[30:33], v[148:151], v[196:199], v[30:33]
	v_mfma_f32_16x16x32_bf16 v[26:29], v[156:159], v[196:199], v[26:29]
	v_mfma_f32_16x16x32_bf16 v[14:17], v[148:151], v[204:207], v[14:17]
	v_mfma_f32_16x16x32_bf16 v[10:13], v[156:159], v[204:207], v[10:13]
	v_mfma_f32_16x16x32_bf16 v[62:65], v[152:155], v[184:187], v[62:65]
	v_mfma_f32_16x16x32_bf16 v[58:61], v[160:163], v[184:187], v[58:61]
	v_mfma_f32_16x16x32_bf16 v[46:49], v[152:155], v[192:195], v[46:49]
	v_mfma_f32_16x16x32_bf16 v[42:45], v[160:163], v[192:195], v[42:45]
	v_mfma_f32_16x16x32_bf16 v[30:33], v[152:155], v[200:203], v[30:33]
	v_mfma_f32_16x16x32_bf16 v[26:29], v[160:163], v[200:203], v[26:29]
	v_mfma_f32_16x16x32_bf16 v[14:17], v[152:155], v[208:211], v[14:17]
	v_mfma_f32_16x16x32_bf16 v[10:13], v[160:163], v[208:211], v[10:13]
	v_mfma_f32_16x16x32_bf16 v[54:57], v[164:167], v[180:183], v[54:57]
	v_mfma_f32_16x16x32_bf16 v[50:53], v[172:175], v[180:183], v[50:53]
	v_mfma_f32_16x16x32_bf16 v[38:41], v[164:167], v[188:191], v[38:41]
	v_mfma_f32_16x16x32_bf16 v[34:37], v[172:175], v[188:191], v[34:37]
	v_mfma_f32_16x16x32_bf16 v[22:25], v[164:167], v[196:199], v[22:25]
	v_mfma_f32_16x16x32_bf16 v[18:21], v[172:175], v[196:199], v[18:21]
	v_mfma_f32_16x16x32_bf16 v[6:9], v[164:167], v[204:207], v[6:9]
	v_mfma_f32_16x16x32_bf16 v[2:5], v[172:175], v[204:207], v[2:5]
	v_mfma_f32_16x16x32_bf16 v[54:57], v[168:171], v[184:187], v[54:57]
	v_mfma_f32_16x16x32_bf16 v[50:53], v[176:179], v[184:187], v[50:53]
	v_mfma_f32_16x16x32_bf16 v[38:41], v[168:171], v[192:195], v[38:41]
	v_mfma_f32_16x16x32_bf16 v[34:37], v[176:179], v[192:195], v[34:37]
	v_mfma_f32_16x16x32_bf16 v[22:25], v[168:171], v[200:203], v[22:25]
	v_mfma_f32_16x16x32_bf16 v[18:21], v[176:179], v[200:203], v[18:21]
	v_mfma_f32_16x16x32_bf16 v[6:9], v[168:171], v[208:211], v[6:9]
	v_mfma_f32_16x16x32_bf16 v[2:5], v[176:179], v[208:211], v[2:5]
	s_barrier
	s_add_i32 s22, s76, 2
	s_add_u32 s20, s20, 0x100
	s_addc_u32 s21, s21, 0
	s_cmp_gt_u32 s76, 29
	s_mov_b32 s76, s22
	s_cbranch_scc1 .LBB0_742

; #define PG8_STAGE(bufoff, gbase, voff) do { _Pragma("unroll") for (int _i = 0; _i < 2; ++_i) \
;         __builtin_amdgcn_global_load_lds((const unsigned*)((const char*)(gbase) + (voff)[_i]), (PG8_LAS unsigned*)(lds + (bufoff) + ldsw + _i * 8192), 16, 0, 0); } while (0)
; #define PG8_LDA(dst, b, h) do { _Pragma("unroll") for (int m = 0; m < 4; ++m) _Pragma("unroll") for (int k = 0; k < 2; ++k) dst[m][k] = *(const PG8_LAS bf16x8*)(lds + PG8_SA(b, h) + aoff + m * 2048 + k * 1024); } while (0)
; #define PG8_LDB(dst, b, h) do { _Pragma("unroll") for (int n = 0; n < 2; ++n) _Pragma("unroll") for (int k = 0; k < 2; ++k) dst[n][k] = *(const PG8_LAS bf16x8*)(lds + PG8_SB(b, h) + boff + n * 2048 + k * 1024); } while (0)
; #define PG8_MMA(ai, bj, At, Bt) do { __builtin_amdgcn_s_setprio(1); _Pragma("unroll") for (int m = 0; m < 4; ++m) _Pragma("unroll") for (int n = 0; n < 2; ++n) _Pragma("unroll") for (int k = 0; k < 2; ++k) \
;         acc[ai][bj][m][n] = __builtin_amdgcn_mfma_f32_16x16x32_bf16(Bt[n][k], At[m][k], acc[ai][bj][m][n], 0, 0, 0); __builtin_amdgcn_s_setprio(0); } while (0)
; #define PG8_WAIT_V(n) asm volatile("s_waitcnt vmcnt(" #n ")" ::: "memory")
; #define PG8_WAIT_L(n) asm volatile("s_waitcnt lgkmcnt(" #n ")" ::: "memory")
; #define PG8_BAR __builtin_amdgcn_s_barrier()
; template <class Epi, class Sched, bool ALIGN_EPI = false, bool SP2 = false>
; __device__ __forceinline__ void gemm_phase(PG8_LAS unsigned char* lds, const Gemm g, const Sched& S, const Epi& E) {
;     ...
;             const char* a1 = cA + (size_t)(t + 1) * kstep;
;             const char* a2 = last ? nA : cA + (size_t)(t + 2) * kstep; const char* b2 = last ? nB : cB + (size_t)(t + 2) * kstep;
;             const char* a3 = a2 + kstep; const char* b3 = b2 + kstep;
;             if (last && has_next) S.a_ready(nxt);
;             if constexpr (SP2) {
;             PG8_LDB(B0, 0, 0); PG8_LDB(B1, 0, 1); PG8_SCHED; PG8_LDA(At, 0, 0); PG8_STAGE(PG8_SA(1, 1), a1 + hstep, voffA);
;             PG8_WAIT_V(8); PG8_WAIT_L(0); PG8_BAR; PG8_MMA(0, 0, At, B0); PG8_MMA(0, 1, At, B1); PG8_BAR; PG8_SCHED;
;             PG8_LDA(At, 0, 1); PG8_STAGE(PG8_SB(0, 0), b2, voffB); PG8_STAGE(PG8_SB(0, 1), b2 + hstep, voffB); PG8_STAGE(PG8_SA(0, 0), a2, voffA);
;             PG8_WAIT_V(8); PG8_WAIT_L(0); PG8_BAR; PG8_MMA(1, 0, At, B0); PG8_MMA(1, 1, At, B1); PG8_BAR; PG8_SCHED;
.LBB0_808:
	s_add_u32 s28, s8, 0xfff80080
	s_addc_u32 s29, s9, -1
	s_add_i32 s48, 0, 0x10000
	s_cmp_eq_u32 s87, 28
	s_cselect_b32 s31, s23, s29
	s_cselect_b32 s30, s67, s28
	v_add_u32_e32 v160, s48, v163
	s_cselect_b32 s29, s21, s86
	s_cselect_b32 s28, s81, s83
	s_add_i32 s91, 0, 0x14000
	ds_read_b128 v[152:155], v160
	ds_read_b128 v[156:159], v160 offset:1024
	ds_read_b128 v[166:169], v160 offset:2048
	ds_read_b128 v[170:173], v160 offset:3072
	v_add_u32_e32 v160, s91, v163
	ds_read_b128 v[174:177], v160
	ds_read_b128 v[178:181], v160 offset:1024
	ds_read_b128 v[182:185], v160 offset:2048
	ds_read_b128 v[186:189], v160 offset:3072
	v_lshl_add_u64 v[160:161], s[8:9], 0, v[148:149]
	s_add_i32 m0, s13, 0xc000
	ds_read_b128 v[190:193], v165
	ds_read_b128 v[194:197], v165 offset:1024
	ds_read_b128 v[198:201], v165 offset:2048
	ds_read_b128 v[202:205], v165 offset:3072
	ds_read_b128 v[206:209], v165 offset:4096
	ds_read_b128 v[210:213], v165 offset:5120
	ds_read_b128 v[214:217], v165 offset:6144
	ds_read_b128 v[224:227], v165 offset:7168
	global_load_lds_dwordx4 v[160:161], off
	s_add_i32 m0, s13, 0xe000
	v_lshl_add_u64 v[160:161], s[8:9], 0, v[150:151]
	global_load_lds_dwordx4 v[160:161], off
	s_waitcnt vmcnt(8) lgkmcnt(0)
	s_barrier
	v_mfma_f32_16x16x32_bf16 v[144:147], v[152:155], v[190:193], v[144:147]
	v_mfma_f32_16x16x32_bf16 v[122:125], v[166:169], v[190:193], v[122:125]
	v_mfma_f32_16x16x32_bf16 v[110:113], v[152:155], v[198:201], v[110:113]
	v_mfma_f32_16x16x32_bf16 v[106:109], v[166:169], v[198:201], v[106:109]
	v_mfma_f32_16x16x32_bf16 v[94:97], v[152:155], v[206:209], v[94:97]
	v_mfma_f32_16x16x32_bf16 v[90:93], v[166:169], v[206:209], v[90:93]
	v_mfma_f32_16x16x32_bf16 v[78:81], v[152:155], v[214:217], v[78:81]
	v_mfma_f32_16x16x32_bf16 v[74:77], v[166:169], v[214:217], v[74:77]
	v_mfma_f32_16x16x32_bf16 v[144:147], v[156:159], v[194:197], v[144:147]
	v_mfma_f32_16x16x32_bf16 v[122:125], v[170:173], v[194:197], v[122:125]
	v_mfma_f32_16x16x32_bf16 v[110:113], v[156:159], v[202:205], v[110:113]
	v_mfma_f32_16x16x32_bf16 v[106:109], v[170:173], v[202:205], v[106:109]
	v_mfma_f32_16x16x32_bf16 v[94:97], v[156:159], v[210:213], v[94:97]
	v_mfma_f32_16x16x32_bf16 v[90:93], v[170:173], v[210:213], v[90:93]
	v_mfma_f32_16x16x32_bf16 v[78:81], v[156:159], v[224:227], v[78:81]
	v_mfma_f32_16x16x32_bf16 v[74:77], v[170:173], v[224:227], v[74:77]
	v_mfma_f32_16x16x32_bf16 v[118:121], v[174:177], v[190:193], v[118:121]
	v_mfma_f32_16x16x32_bf16 v[114:117], v[182:185], v[190:193], v[114:117]
	v_mfma_f32_16x16x32_bf16 v[102:105], v[174:177], v[198:201], v[102:105]
	v_mfma_f32_16x16x32_bf16 v[98:101], v[182:185], v[198:201], v[98:101]
	v_mfma_f32_16x16x32_bf16 v[86:89], v[174:177], v[206:209], v[86:89]
	v_mfma_f32_16x16x32_bf16 v[82:85], v[182:185], v[206:209], v[82:85]
	v_mfma_f32_16x16x32_bf16 v[70:73], v[174:177], v[214:217], v[70:73]
	v_mfma_f32_16x16x32_bf16 v[66:69], v[182:185], v[214:217], v[66:69]
	v_mfma_f32_16x16x32_bf16 v[118:121], v[178:181], v[194:197], v[118:121]
	v_mfma_f32_16x16x32_bf16 v[114:117], v[186:189], v[194:197], v[114:117]
	v_mfma_f32_16x16x32_bf16 v[102:105], v[178:181], v[202:205], v[102:105]
	v_mfma_f32_16x16x32_bf16 v[98:101], v[186:189], v[202:205], v[98:101]
	v_mfma_f32_16x16x32_bf16 v[86:89], v[178:181], v[210:213], v[86:89]
	v_mfma_f32_16x16x32_bf16 v[82:85], v[186:189], v[210:213], v[82:85]
	v_mfma_f32_16x16x32_bf16 v[70:73], v[178:181], v[224:227], v[70:73]
	v_mfma_f32_16x16x32_bf16 v[66:69], v[186:189], v[224:227], v[66:69]
	s_barrier
	s_add_i32 s48, s48, s12
	v_lshl_add_u64 v[160:161], s[28:29], 0, v[0:1]
	s_mov_b32 m0, s48
	ds_read_b128 v[190:193], v165 offset:16384
	ds_read_b128 v[194:197], v165 offset:17408
	ds_read_b128 v[198:201], v165 offset:18432
	ds_read_b128 v[202:205], v165 offset:19456
	ds_read_b128 v[206:209], v165 offset:20480
	ds_read_b128 v[210:213], v165 offset:21504
	ds_read_b128 v[214:217], v165 offset:22528
	ds_read_b128 v[224:227], v165 offset:23552
	global_load_lds_dwordx4 v[160:161], off
	s_add_i32 m0, s48, 0x2000
	s_add_u32 vcc_lo, s28, 0x80000
	v_lshl_add_u64 v[218:219], s[28:29], 0, v[126:127]
	s_addc_u32 vcc_hi, s29, 0
	s_add_i32 s48, s91, s12
	global_load_lds_dwordx4 v[218:219], off
	v_lshl_add_u64 v[220:221], vcc, 0, v[0:1]
	s_mov_b32 m0, s48
	v_lshl_add_u64 v[222:223], s[30:31], 0, v[126:127]
	global_load_lds_dwordx4 v[220:221], off
	s_add_i32 m0, s48, 0x2000
	v_lshl_add_u64 v[220:221], vcc, 0, v[126:127]
	global_load_lds_dwordx4 v[220:221], off
	s_mov_b32 m0, s13
	v_lshl_add_u64 v[220:221], s[30:31], 0, v[0:1]
	global_load_lds_dwordx4 v[220:221], off
	s_mov_b32 m0, s34
	s_nop 0
	global_load_lds_dwordx4 v[222:223], off
	s_waitcnt vmcnt(8) lgkmcnt(0)
	s_barrier
; #define PG8_STAGE(bufoff, gbase, voff) do { _Pragma("unroll") for (int _i = 0; _i < 2; ++_i) \
;         __builtin_amdgcn_global_load_lds((const unsigned*)((const char*)(gbase) + (voff)[_i]), (PG8_LAS unsigned*)(lds + (bufoff) + ldsw + _i * 8192), 16, 0, 0); } while (0)
; #define PG8_LDA(dst, b, h) do { _Pragma("unroll") for (int m = 0; m < 4; ++m) _Pragma("unroll") for (int k = 0; k < 2; ++k) dst[m][k] = *(const PG8_LAS bf16x8*)(lds + PG8_SA(b, h) + aoff + m * 2048 + k * 1024); } while (0)
; #define PG8_LDB(dst, b, h) do { _Pragma("unroll") for (int n = 0; n < 2; ++n) _Pragma("unroll") for (int k = 0; k < 2; ++k) dst[n][k] = *(const PG8_LAS bf16x8*)(lds + PG8_SB(b, h) + boff + n * 2048 + k * 1024); } while (0)
; #define PG8_MMA(ai, bj, At, Bt) do { __builtin_amdgcn_s_setprio(1); _Pragma("unroll") for (int m = 0; m < 4; ++m) _Pragma("unroll") for (int n = 0; n < 2; ++n) _Pragma("unroll") for (int k = 0; k < 2; ++k) \
;         acc[ai][bj][m][n] = __builtin_amdgcn_mfma_f32_16x16x32_bf16(Bt[n][k], At[m][k], acc[ai][bj][m][n], 0, 0, 0); __builtin_amdgcn_s_setprio(0); } while (0)
; #define PG8_WAIT_V(n) asm volatile("s_waitcnt vmcnt(" #n ")" ::: "memory")
; #define PG8_WAIT_L(n) asm volatile("s_waitcnt lgkmcnt(" #n ")" ::: "memory")
; #define PG8_BAR __builtin_amdgcn_s_barrier()
; #define PG8_SCHED __builtin_amdgcn_sched_barrier(0)
; template <class Epi, class Sched, bool ALIGN_EPI = false, bool SP2 = false>
; __device__ __forceinline__ void gemm_phase(PG8_LAS unsigned char* lds, const Gemm g, const Sched& S, const Epi& E) {
;     ...
;             PG8_WAIT_V(8); PG8_WAIT_L(0); PG8_BAR; PG8_MMA(0, 0, At, B0); PG8_MMA(0, 1, At, B1); PG8_BAR; PG8_SCHED;
;             PG8_LDA(At, 0, 1); PG8_STAGE(PG8_SB(0, 0), b2, voffB); PG8_STAGE(PG8_SB(0, 1), b2 + hstep, voffB); PG8_STAGE(PG8_SA(0, 0), a2, voffA);
;             PG8_WAIT_V(8); PG8_WAIT_L(0); PG8_BAR; PG8_MMA(1, 0, At, B0); PG8_MMA(1, 1, At, B1); PG8_BAR; PG8_SCHED;
;             PG8_LDB(B0, 1, 0); PG8_LDB(B1, 1, 1); PG8_SCHED; PG8_LDA(At, 1, 0); PG8_STAGE(PG8_SA(0, 1), a2 + hstep, voffA);
;             PG8_WAIT_V(8); PG8_WAIT_L(0); PG8_BAR; PG8_MMA(0, 0, At, B0); PG8_MMA(0, 1, At, B1); PG8_BAR; PG8_SCHED;
	v_mfma_f32_16x16x32_bf16 v[62:65], v[152:155], v[190:193], v[62:65]
	v_mfma_f32_16x16x32_bf16 v[58:61], v[166:169], v[190:193], v[58:61]
	v_mfma_f32_16x16x32_bf16 v[46:49], v[152:155], v[198:201], v[46:49]
	v_mfma_f32_16x16x32_bf16 v[42:45], v[166:169], v[198:201], v[42:45]
	v_mfma_f32_16x16x32_bf16 v[30:33], v[152:155], v[206:209], v[30:33]
	v_mfma_f32_16x16x32_bf16 v[26:29], v[166:169], v[206:209], v[26:29]
	v_mfma_f32_16x16x32_bf16 v[14:17], v[152:155], v[214:217], v[14:17]
	v_mfma_f32_16x16x32_bf16 v[10:13], v[166:169], v[214:217], v[10:13]
	v_mfma_f32_16x16x32_bf16 v[62:65], v[156:159], v[194:197], v[62:65]
	v_mfma_f32_16x16x32_bf16 v[58:61], v[170:173], v[194:197], v[58:61]
	v_mfma_f32_16x16x32_bf16 v[46:49], v[156:159], v[202:205], v[46:49]
	v_mfma_f32_16x16x32_bf16 v[42:45], v[170:173], v[202:205], v[42:45]
	v_mfma_f32_16x16x32_bf16 v[30:33], v[156:159], v[210:213], v[30:33]
	v_mfma_f32_16x16x32_bf16 v[26:29], v[170:173], v[210:213], v[26:29]
	v_mfma_f32_16x16x32_bf16 v[14:17], v[156:159], v[224:227], v[14:17]
	v_mfma_f32_16x16x32_bf16 v[10:13], v[170:173], v[224:227], v[10:13]
	v_mfma_f32_16x16x32_bf16 v[54:57], v[174:177], v[190:193], v[54:57]
	v_mfma_f32_16x16x32_bf16 v[50:53], v[182:185], v[190:193], v[50:53]
	v_mfma_f32_16x16x32_bf16 v[38:41], v[174:177], v[198:201], v[38:41]
	v_mfma_f32_16x16x32_bf16 v[34:37], v[182:185], v[198:201], v[34:37]
	v_mfma_f32_16x16x32_bf16 v[22:25], v[174:177], v[206:209], v[22:25]
	v_mfma_f32_16x16x32_bf16 v[18:21], v[182:185], v[206:209], v[18:21]
	v_mfma_f32_16x16x32_bf16 v[6:9], v[174:177], v[214:217], v[6:9]
	v_mfma_f32_16x16x32_bf16 v[2:5], v[182:185], v[214:217], v[2:5]
	v_mfma_f32_16x16x32_bf16 v[54:57], v[178:181], v[194:197], v[54:57]
	v_mfma_f32_16x16x32_bf16 v[50:53], v[186:189], v[194:197], v[50:53]
	v_mfma_f32_16x16x32_bf16 v[38:41], v[178:181], v[202:205], v[38:41]
	v_mfma_f32_16x16x32_bf16 v[34:37], v[186:189], v[202:205], v[34:37]
	v_mfma_f32_16x16x32_bf16 v[22:25], v[178:181], v[210:213], v[22:25]
	v_mfma_f32_16x16x32_bf16 v[18:21], v[186:189], v[210:213], v[18:21]
	v_mfma_f32_16x16x32_bf16 v[6:9], v[178:181], v[224:227], v[6:9]
	v_mfma_f32_16x16x32_bf16 v[2:5], v[186:189], v[224:227], v[2:5]
	s_barrier
	s_add_i32 s48, 0, 0x18000
	s_add_i32 s91, 0, 0x1c000
	v_add_u32_e32 v170, s48, v163
	v_add_u32_e32 v186, s91, v163
	ds_read_b128 v[152:155], v170
	ds_read_b128 v[156:159], v170 offset:1024
	ds_read_b128 v[166:169], v170 offset:2048
	ds_read_b128 v[170:173], v170 offset:3072
	ds_read_b128 v[174:177], v186
	ds_read_b128 v[178:181], v186 offset:1024
	ds_read_b128 v[182:185], v186 offset:2048
	ds_read_b128 v[186:189], v186 offset:3072
	s_add_u32 s30, s30, 0x80000
	s_addc_u32 s31, s31, 0
	s_mov_b32 m0, s35
	v_lshl_add_u64 v[228:229], s[30:31], 0, v[0:1]
	ds_read_b128 v[190:193], v165 offset:32768
	ds_read_b128 v[194:197], v165 offset:33792
	ds_read_b128 v[198:201], v165 offset:34816
	ds_read_b128 v[202:205], v165 offset:35840
	ds_read_b128 v[206:209], v165 offset:36864
	ds_read_b128 v[210:213], v165 offset:37888
	ds_read_b128 v[214:217], v165 offset:38912
	ds_read_b128 v[224:227], v165 offset:39936
	global_load_lds_dwordx4 v[228:229], off
	s_mov_b32 m0, s42
	v_lshl_add_u64 v[228:229], s[30:31], 0, v[126:127]
	global_load_lds_dwordx4 v[228:229], off
	s_waitcnt vmcnt(8) lgkmcnt(0)
	s_barrier
	v_mfma_f32_16x16x32_bf16 v[144:147], v[152:155], v[190:193], v[144:147]
	v_mfma_f32_16x16x32_bf16 v[122:125], v[166:169], v[190:193], v[122:125]
	v_mfma_f32_16x16x32_bf16 v[110:113], v[152:155], v[198:201], v[110:113]
	v_mfma_f32_16x16x32_bf16 v[106:109], v[166:169], v[198:201], v[106:109]
	v_mfma_f32_16x16x32_bf16 v[94:97], v[152:155], v[206:209], v[94:97]
	v_mfma_f32_16x16x32_bf16 v[90:93], v[166:169], v[206:209], v[90:93]
	v_mfma_f32_16x16x32_bf16 v[78:81], v[152:155], v[214:217], v[78:81]
	v_mfma_f32_16x16x32_bf16 v[74:77], v[166:169], v[214:217], v[74:77]
	v_mfma_f32_16x16x32_bf16 v[144:147], v[156:159], v[194:197], v[144:147]
	v_mfma_f32_16x16x32_bf16 v[122:125], v[170:173], v[194:197], v[122:125]
	v_mfma_f32_16x16x32_bf16 v[110:113], v[156:159], v[202:205], v[110:113]
	v_mfma_f32_16x16x32_bf16 v[106:109], v[170:173], v[202:205], v[106:109]
	v_mfma_f32_16x16x32_bf16 v[94:97], v[156:159], v[210:213], v[94:97]
	v_mfma_f32_16x16x32_bf16 v[90:93], v[170:173], v[210:213], v[90:93]
	v_mfma_f32_16x16x32_bf16 v[78:81], v[156:159], v[224:227], v[78:81]
	v_mfma_f32_16x16x32_bf16 v[74:77], v[170:173], v[224:227], v[74:77]
	v_mfma_f32_16x16x32_bf16 v[118:121], v[174:177], v[190:193], v[118:121]
	v_mfma_f32_16x16x32_bf16 v[114:117], v[182:185], v[190:193], v[114:117]
	v_mfma_f32_16x16x32_bf16 v[102:105], v[174:177], v[198:201], v[102:105]
	v_mfma_f32_16x16x32_bf16 v[98:101], v[182:185], v[198:201], v[98:101]
	v_mfma_f32_16x16x32_bf16 v[86:89], v[174:177], v[206:209], v[86:89]
	v_mfma_f32_16x16x32_bf16 v[82:85], v[182:185], v[206:209], v[82:85]
	v_mfma_f32_16x16x32_bf16 v[70:73], v[174:177], v[214:217], v[70:73]
	v_mfma_f32_16x16x32_bf16 v[66:69], v[182:185], v[214:217], v[66:69]
	v_mfma_f32_16x16x32_bf16 v[118:121], v[178:181], v[194:197], v[118:121]
	v_mfma_f32_16x16x32_bf16 v[114:117], v[186:189], v[194:197], v[114:117]
	v_mfma_f32_16x16x32_bf16 v[102:105], v[178:181], v[202:205], v[102:105]
	v_mfma_f32_16x16x32_bf16 v[98:101], v[186:189], v[202:205], v[98:101]
	v_mfma_f32_16x16x32_bf16 v[86:89], v[178:181], v[210:213], v[86:89]
	v_mfma_f32_16x16x32_bf16 v[82:85], v[186:189], v[210:213], v[82:85]
	v_mfma_f32_16x16x32_bf16 v[70:73], v[178:181], v[224:227], v[70:73]
	v_mfma_f32_16x16x32_bf16 v[66:69], v[186:189], v[224:227], v[66:69]
	s_barrier
; #define PG8_STAGE(bufoff, gbase, voff) do { _Pragma("unroll") for (int _i = 0; _i < 2; ++_i) \
;         __builtin_amdgcn_global_load_lds((const unsigned*)((const char*)(gbase) + (voff)[_i]), (PG8_LAS unsigned*)(lds + (bufoff) + ldsw + _i * 8192), 16, 0, 0); } while (0)
; #define PG8_LDA(dst, b, h) do { _Pragma("unroll") for (int m = 0; m < 4; ++m) _Pragma("unroll") for (int k = 0; k < 2; ++k) dst[m][k] = *(const PG8_LAS bf16x8*)(lds + PG8_SA(b, h) + aoff + m * 2048 + k * 1024); } while (0)
; #define PG8_MMA(ai, bj, At, Bt) do { __builtin_amdgcn_s_setprio(1); _Pragma("unroll") for (int m = 0; m < 4; ++m) _Pragma("unroll") for (int n = 0; n < 2; ++n) _Pragma("unroll") for (int k = 0; k < 2; ++k) \
;         acc[ai][bj][m][n] = __builtin_amdgcn_mfma_f32_16x16x32_bf16(Bt[n][k], At[m][k], acc[ai][bj][m][n], 0, 0, 0); __builtin_amdgcn_s_setprio(0); } while (0)
; #define PG8_WAIT_V(n) asm volatile("s_waitcnt vmcnt(" #n ")" ::: "memory")
; #define PG8_WAIT_L(n) asm volatile("s_waitcnt lgkmcnt(" #n ")" ::: "memory")
; #define PG8_BAR __builtin_amdgcn_s_barrier()
; #define PG8_SCHED __builtin_amdgcn_sched_barrier(0)
; template <class Epi, class Sched, bool ALIGN_EPI = false, bool SP2 = false>
; __device__ __forceinline__ void gemm_phase(PG8_LAS unsigned char* lds, const Gemm g, const Sched& S, const Epi& E) {
;     ...
;         for (int t = 0; t < nt; t += 2) {
;     ...
;             PG8_WAIT_V(8); PG8_WAIT_L(0); PG8_BAR; PG8_MMA(0, 0, At, B0); PG8_MMA(0, 1, At, B1); PG8_BAR; PG8_SCHED;
;             PG8_LDA(At, 1, 1); PG8_STAGE(PG8_SB(1, 0), b3, voffB); PG8_STAGE(PG8_SB(1, 1), b3 + hstep, voffB); PG8_STAGE(PG8_SA(1, 0), a3, voffA);
;             PG8_WAIT_V(8); PG8_WAIT_L(0); PG8_BAR; PG8_MMA(1, 0, At, B0); PG8_MMA(1, 1, At, B1); PG8_BAR; PG8_SCHED;
	s_add_i32 s30, s48, s12
	v_lshl_add_u64 v[160:161], v[160:161], 0, s[64:65]
	s_mov_b32 m0, s30
	ds_read_b128 v[190:193], v165 offset:49152
	ds_read_b128 v[194:197], v165 offset:50176
	ds_read_b128 v[198:201], v165 offset:51200
	ds_read_b128 v[202:205], v165 offset:52224
	ds_read_b128 v[206:209], v165 offset:53248
	ds_read_b128 v[210:213], v165 offset:54272
	ds_read_b128 v[214:217], v165 offset:55296
	ds_read_b128 v[224:227], v165 offset:56320
	global_load_lds_dwordx4 v[160:161], off
	s_add_i32 m0, s30, 0x2000
	s_add_u32 s28, s28, 0x80080
	v_lshl_add_u64 v[160:161], v[218:219], 0, s[64:65]
	s_addc_u32 s29, s29, 0
	s_add_i32 s30, s91, s12
	global_load_lds_dwordx4 v[160:161], off
	s_mov_b32 m0, s30
	v_lshl_add_u64 v[160:161], s[28:29], 0, v[0:1]
	global_load_lds_dwordx4 v[160:161], off
	s_add_i32 m0, s30, 0x2000
	v_lshl_add_u64 v[160:161], s[28:29], 0, v[126:127]
	global_load_lds_dwordx4 v[160:161], off
	s_mov_b32 m0, s43
	v_lshl_add_u64 v[160:161], v[220:221], 0, s[64:65]
	global_load_lds_dwordx4 v[160:161], off
	s_mov_b32 m0, s76
	v_lshl_add_u64 v[160:161], v[222:223], 0, s[64:65]
	global_load_lds_dwordx4 v[160:161], off
	s_waitcnt vmcnt(8) lgkmcnt(0)
	s_barrier
	v_mfma_f32_16x16x32_bf16 v[62:65], v[152:155], v[190:193], v[62:65]
	v_mfma_f32_16x16x32_bf16 v[58:61], v[166:169], v[190:193], v[58:61]
	v_mfma_f32_16x16x32_bf16 v[46:49], v[152:155], v[198:201], v[46:49]
	v_mfma_f32_16x16x32_bf16 v[42:45], v[166:169], v[198:201], v[42:45]
	v_mfma_f32_16x16x32_bf16 v[30:33], v[152:155], v[206:209], v[30:33]
	v_mfma_f32_16x16x32_bf16 v[26:29], v[166:169], v[206:209], v[26:29]
	v_mfma_f32_16x16x32_bf16 v[14:17], v[152:155], v[214:217], v[14:17]
	v_mfma_f32_16x16x32_bf16 v[10:13], v[166:169], v[214:217], v[10:13]
	v_mfma_f32_16x16x32_bf16 v[62:65], v[156:159], v[194:197], v[62:65]
	v_mfma_f32_16x16x32_bf16 v[58:61], v[170:173], v[194:197], v[58:61]
	v_mfma_f32_16x16x32_bf16 v[46:49], v[156:159], v[202:205], v[46:49]
	v_mfma_f32_16x16x32_bf16 v[42:45], v[170:173], v[202:205], v[42:45]
	v_mfma_f32_16x16x32_bf16 v[30:33], v[156:159], v[210:213], v[30:33]
	v_mfma_f32_16x16x32_bf16 v[26:29], v[170:173], v[210:213], v[26:29]
	v_mfma_f32_16x16x32_bf16 v[14:17], v[156:159], v[224:227], v[14:17]
	v_mfma_f32_16x16x32_bf16 v[10:13], v[170:173], v[224:227], v[10:13]
	v_mfma_f32_16x16x32_bf16 v[54:57], v[174:177], v[190:193], v[54:57]
	v_mfma_f32_16x16x32_bf16 v[50:53], v[182:185], v[190:193], v[50:53]
	v_mfma_f32_16x16x32_bf16 v[38:41], v[174:177], v[198:201], v[38:41]
	v_mfma_f32_16x16x32_bf16 v[34:37], v[182:185], v[198:201], v[34:37]
	v_mfma_f32_16x16x32_bf16 v[22:25], v[174:177], v[206:209], v[22:25]
	v_mfma_f32_16x16x32_bf16 v[18:21], v[182:185], v[206:209], v[18:21]
	v_mfma_f32_16x16x32_bf16 v[6:9], v[174:177], v[214:217], v[6:9]
	v_mfma_f32_16x16x32_bf16 v[2:5], v[182:185], v[214:217], v[2:5]
	v_mfma_f32_16x16x32_bf16 v[54:57], v[178:181], v[194:197], v[54:57]
	v_mfma_f32_16x16x32_bf16 v[50:53], v[186:189], v[194:197], v[50:53]
	v_mfma_f32_16x16x32_bf16 v[38:41], v[178:181], v[202:205], v[38:41]
	v_mfma_f32_16x16x32_bf16 v[34:37], v[186:189], v[202:205], v[34:37]
	v_mfma_f32_16x16x32_bf16 v[22:25], v[178:181], v[210:213], v[22:25]
	v_mfma_f32_16x16x32_bf16 v[18:21], v[186:189], v[210:213], v[18:21]
	v_mfma_f32_16x16x32_bf16 v[6:9], v[178:181], v[224:227], v[6:9]
	v_mfma_f32_16x16x32_bf16 v[2:5], v[186:189], v[224:227], v[2:5]
	s_barrier
	s_add_i32 s87, s87, 2
	s_add_u32 s8, s8, 0x100
	s_addc_u32 s9, s9, 0
	s_add_u32 s83, s83, 0x100
	s_addc_u32 s86, s86, 0
	s_cmp_gt_u32 s87, 29
	s_cbranch_scc0 .LBB0_808
	s_and_b64 vcc, exec, s[18:19]
	s_cbranch_vccz .LBB0_811
	s_barrier

; #define PG8_STAGE(bufoff, gbase, voff) do { _Pragma("unroll") for (int _i = 0; _i < 2; ++_i) \
;         __builtin_amdgcn_global_load_lds((const unsigned*)((const char*)(gbase) + (voff)[_i]), (PG8_LAS unsigned*)(lds + (bufoff) + ldsw + _i * 8192), 16, 0, 0); } while (0)
; #define PG8_LDA(dst, b, h) do { _Pragma("unroll") for (int m = 0; m < 4; ++m) _Pragma("unroll") for (int k = 0; k < 2; ++k) dst[m][k] = *(const PG8_LAS bf16x8*)(lds + PG8_SA(b, h) + aoff + m * 2048 + k * 1024); } while (0)
; #define PG8_LDB(dst, b, h) do { _Pragma("unroll") for (int n = 0; n < 2; ++n) _Pragma("unroll") for (int k = 0; k < 2; ++k) dst[n][k] = *(const PG8_LAS bf16x8*)(lds + PG8_SB(b, h) + boff + n * 2048 + k * 1024); } while (0)
; #define PG8_MMA(ai, bj, At, Bt) do { __builtin_amdgcn_s_setprio(1); _Pragma("unroll") for (int m = 0; m < 4; ++m) _Pragma("unroll") for (int n = 0; n < 2; ++n) _Pragma("unroll") for (int k = 0; k < 2; ++k) \
;         acc[ai][bj][m][n] = __builtin_amdgcn_mfma_f32_16x16x32_bf16(Bt[n][k], At[m][k], acc[ai][bj][m][n], 0, 0, 0); __builtin_amdgcn_s_setprio(0); } while (0)
; #define PG8_WAIT_V(n) asm volatile("s_waitcnt vmcnt(" #n ")" ::: "memory")
; #define PG8_WAIT_L(n) asm volatile("s_waitcnt lgkmcnt(" #n ")" ::: "memory")
; #define PG8_BAR __builtin_amdgcn_s_barrier()
; template <class Epi, class Sched, bool ALIGN_EPI = false, bool SP2 = false>
; __device__ __forceinline__ void gemm_phase(PG8_LAS unsigned char* lds, const Gemm g, const Sched& S, const Epi& E) {
;     ...
;             const char* a1 = cA + (size_t)(t + 1) * kstep;
;             const char* a2 = last ? nA : cA + (size_t)(t + 2) * kstep; const char* b2 = last ? nB : cB + (size_t)(t + 2) * kstep;
;             const char* a3 = a2 + kstep; const char* b3 = b2 + kstep;
;             if (last && has_next) S.a_ready(nxt);
;             if constexpr (SP2) {
;             PG8_LDB(B0, 0, 0); PG8_LDB(B1, 0, 1); PG8_SCHED; PG8_LDA(At, 0, 0); PG8_STAGE(PG8_SA(1, 1), a1 + hstep, voffA);
;             PG8_WAIT_V(8); PG8_WAIT_L(0); PG8_BAR; PG8_MMA(0, 0, At, B0); PG8_MMA(0, 1, At, B1); PG8_BAR; PG8_SCHED;
;             PG8_LDA(At, 0, 1); PG8_STAGE(PG8_SB(0, 0), b2, voffB); PG8_STAGE(PG8_SB(0, 1), b2 + hstep, voffB); PG8_STAGE(PG8_SA(0, 0), a2, voffA);
;             PG8_WAIT_V(8); PG8_WAIT_L(0); PG8_BAR; PG8_MMA(1, 0, At, B0); PG8_MMA(1, 1, At, B1); PG8_BAR; PG8_SCHED;
.LBB0_910:
	s_add_u32 s28, s0, 0xfff80080
	s_addc_u32 s29, s1, -1
	s_add_i32 s48, 0, 0x10000
	s_cmp_eq_u32 s81, 28
	s_cselect_b32 s31, s21, s29
	s_cselect_b32 s30, s35, s28
	s_cselect_b32 s29, s23, s67
	s_cselect_b32 s28, s40, s41
	s_add_i32 s91, 0, 0x14000
	v_add_u32_e32 v164, s48, v179
	v_add_u32_e32 v176, s91, v179
	ds_read_b128 v[152:155], v164
	ds_read_b128 v[156:159], v164 offset:1024
	ds_read_b128 v[160:163], v164 offset:2048
	ds_read_b128 v[164:167], v164 offset:3072
	ds_read_b128 v[168:171], v176
	ds_read_b128 v[172:175], v176 offset:1024
	ds_read_b128 v[182:185], v176 offset:2048
	ds_read_b128 v[186:189], v176 offset:3072
	v_lshl_add_u64 v[176:177], s[0:1], 0, v[148:149]
	s_add_i32 m0, s43, 0xc000
	ds_read_b128 v[190:193], v181
	ds_read_b128 v[194:197], v181 offset:1024
	ds_read_b128 v[198:201], v181 offset:2048
	ds_read_b128 v[202:205], v181 offset:3072
	ds_read_b128 v[206:209], v181 offset:4096
	ds_read_b128 v[210:213], v181 offset:5120
	ds_read_b128 v[214:217], v181 offset:6144
	ds_read_b128 v[224:227], v181 offset:7168
	global_load_lds_dwordx4 v[176:177], off
	s_add_i32 m0, s43, 0xe000
	v_lshl_add_u64 v[176:177], s[0:1], 0, v[150:151]
	global_load_lds_dwordx4 v[176:177], off
	s_waitcnt vmcnt(8) lgkmcnt(0)
	s_barrier
	v_mfma_f32_16x16x32_bf16 v[74:77], v[152:155], v[190:193], v[74:77]
	v_mfma_f32_16x16x32_bf16 v[78:81], v[160:163], v[190:193], v[78:81]
	v_mfma_f32_16x16x32_bf16 v[102:105], v[152:155], v[198:201], v[102:105]
	v_mfma_f32_16x16x32_bf16 v[106:109], v[160:163], v[198:201], v[106:109]
	v_mfma_f32_16x16x32_bf16 v[122:125], v[152:155], v[206:209], v[122:125]
	v_mfma_f32_16x16x32_bf16 v[144:147], v[160:163], v[206:209], v[144:147]
	v_mfma_f32_16x16x32_bf16 v[90:93], v[152:155], v[214:217], v[90:93]
	v_mfma_f32_16x16x32_bf16 v[86:89], v[160:163], v[214:217], v[86:89]
	v_mfma_f32_16x16x32_bf16 v[74:77], v[156:159], v[194:197], v[74:77]
	v_mfma_f32_16x16x32_bf16 v[78:81], v[164:167], v[194:197], v[78:81]
	v_mfma_f32_16x16x32_bf16 v[102:105], v[156:159], v[202:205], v[102:105]
	v_mfma_f32_16x16x32_bf16 v[106:109], v[164:167], v[202:205], v[106:109]
	v_mfma_f32_16x16x32_bf16 v[122:125], v[156:159], v[210:213], v[122:125]
	v_mfma_f32_16x16x32_bf16 v[144:147], v[164:167], v[210:213], v[144:147]
	v_mfma_f32_16x16x32_bf16 v[90:93], v[156:159], v[224:227], v[90:93]
	v_mfma_f32_16x16x32_bf16 v[86:89], v[164:167], v[224:227], v[86:89]
	v_mfma_f32_16x16x32_bf16 v[82:85], v[168:171], v[190:193], v[82:85]
	v_mfma_f32_16x16x32_bf16 v[94:97], v[182:185], v[190:193], v[94:97]
	v_mfma_f32_16x16x32_bf16 v[110:113], v[168:171], v[198:201], v[110:113]
	v_mfma_f32_16x16x32_bf16 v[118:121], v[182:185], v[198:201], v[118:121]
	v_mfma_f32_16x16x32_bf16 v[114:117], v[168:171], v[206:209], v[114:117]
	v_mfma_f32_16x16x32_bf16 v[98:101], v[182:185], v[206:209], v[98:101]
	v_mfma_f32_16x16x32_bf16 v[70:73], v[168:171], v[214:217], v[70:73]
	v_mfma_f32_16x16x32_bf16 v[66:69], v[182:185], v[214:217], v[66:69]
	v_mfma_f32_16x16x32_bf16 v[82:85], v[172:175], v[194:197], v[82:85]
	v_mfma_f32_16x16x32_bf16 v[94:97], v[186:189], v[194:197], v[94:97]
	v_mfma_f32_16x16x32_bf16 v[110:113], v[172:175], v[202:205], v[110:113]
	v_mfma_f32_16x16x32_bf16 v[118:121], v[186:189], v[202:205], v[118:121]
	v_mfma_f32_16x16x32_bf16 v[114:117], v[172:175], v[210:213], v[114:117]
	v_mfma_f32_16x16x32_bf16 v[98:101], v[186:189], v[210:213], v[98:101]
	v_mfma_f32_16x16x32_bf16 v[70:73], v[172:175], v[224:227], v[70:73]
	v_mfma_f32_16x16x32_bf16 v[66:69], v[186:189], v[224:227], v[66:69]
	s_barrier
	s_add_i32 s48, s48, s42
	v_lshl_add_u64 v[176:177], s[28:29], 0, v[0:1]
	s_mov_b32 m0, s48
	ds_read_b128 v[190:193], v181 offset:16384
	ds_read_b128 v[194:197], v181 offset:17408
	ds_read_b128 v[198:201], v181 offset:18432
	ds_read_b128 v[202:205], v181 offset:19456
	ds_read_b128 v[206:209], v181 offset:20480
	ds_read_b128 v[210:213], v181 offset:21504
	ds_read_b128 v[214:217], v181 offset:22528
	ds_read_b128 v[224:227], v181 offset:23552
	global_load_lds_dwordx4 v[176:177], off
	s_add_i32 m0, s48, 0x2000
	s_add_u32 vcc_lo, s28, 0x80000
	v_lshl_add_u64 v[218:219], s[28:29], 0, v[126:127]
	s_addc_u32 vcc_hi, s29, 0
	s_add_i32 s48, s91, s42
	global_load_lds_dwordx4 v[218:219], off
	v_lshl_add_u64 v[220:221], vcc, 0, v[0:1]
	s_mov_b32 m0, s48
	v_lshl_add_u64 v[222:223], s[30:31], 0, v[126:127]
	global_load_lds_dwordx4 v[220:221], off
	s_add_i32 m0, s48, 0x2000
	v_lshl_add_u64 v[220:221], vcc, 0, v[126:127]
	global_load_lds_dwordx4 v[220:221], off
	s_mov_b32 m0, s43
	v_lshl_add_u64 v[220:221], s[30:31], 0, v[0:1]
	global_load_lds_dwordx4 v[220:221], off
	s_mov_b32 m0, s76
	s_nop 0
	global_load_lds_dwordx4 v[222:223], off
	s_waitcnt vmcnt(8) lgkmcnt(0)
	s_barrier
; #define PG8_STAGE(bufoff, gbase, voff) do { _Pragma("unroll") for (int _i = 0; _i < 2; ++_i) \
;         __builtin_amdgcn_global_load_lds((const unsigned*)((const char*)(gbase) + (voff)[_i]), (PG8_LAS unsigned*)(lds + (bufoff) + ldsw + _i * 8192), 16, 0, 0); } while (0)
; #define PG8_LDA(dst, b, h) do { _Pragma("unroll") for (int m = 0; m < 4; ++m) _Pragma("unroll") for (int k = 0; k < 2; ++k) dst[m][k] = *(const PG8_LAS bf16x8*)(lds + PG8_SA(b, h) + aoff + m * 2048 + k * 1024); } while (0)
; #define PG8_LDB(dst, b, h) do { _Pragma("unroll") for (int n = 0; n < 2; ++n) _Pragma("unroll") for (int k = 0; k < 2; ++k) dst[n][k] = *(const PG8_LAS bf16x8*)(lds + PG8_SB(b, h) + boff + n * 2048 + k * 1024); } while (0)
; #define PG8_MMA(ai, bj, At, Bt) do { __builtin_amdgcn_s_setprio(1); _Pragma("unroll") for (int m = 0; m < 4; ++m) _Pragma("unroll") for (int n = 0; n < 2; ++n) _Pragma("unroll") for (int k = 0; k < 2; ++k) \
;         acc[ai][bj][m][n] = __builtin_amdgcn_mfma_f32_16x16x32_bf16(Bt[n][k], At[m][k], acc[ai][bj][m][n], 0, 0, 0); __builtin_amdgcn_s_setprio(0); } while (0)
; #define PG8_WAIT_V(n) asm volatile("s_waitcnt vmcnt(" #n ")" ::: "memory")
; #define PG8_WAIT_L(n) asm volatile("s_waitcnt lgkmcnt(" #n ")" ::: "memory")
; #define PG8_BAR __builtin_amdgcn_s_barrier()
; #define PG8_SCHED __builtin_amdgcn_sched_barrier(0)
; template <class Epi, class Sched, bool ALIGN_EPI = false, bool SP2 = false>
; __device__ __forceinline__ void gemm_phase(PG8_LAS unsigned char* lds, const Gemm g, const Sched& S, const Epi& E) {
;     ...
;             PG8_WAIT_V(8); PG8_WAIT_L(0); PG8_BAR; PG8_MMA(0, 0, At, B0); PG8_MMA(0, 1, At, B1); PG8_BAR; PG8_SCHED;
;             PG8_LDA(At, 0, 1); PG8_STAGE(PG8_SB(0, 0), b2, voffB); PG8_STAGE(PG8_SB(0, 1), b2 + hstep, voffB); PG8_STAGE(PG8_SA(0, 0), a2, voffA);
;             PG8_WAIT_V(8); PG8_WAIT_L(0); PG8_BAR; PG8_MMA(1, 0, At, B0); PG8_MMA(1, 1, At, B1); PG8_BAR; PG8_SCHED;
;             PG8_LDB(B0, 1, 0); PG8_LDB(B1, 1, 1); PG8_SCHED; PG8_LDA(At, 1, 0); PG8_STAGE(PG8_SA(0, 1), a2 + hstep, voffA);
;             PG8_WAIT_V(8); PG8_WAIT_L(0); PG8_BAR; PG8_MMA(0, 0, At, B0); PG8_MMA(0, 1, At, B1); PG8_BAR; PG8_SCHED;
	v_mfma_f32_16x16x32_bf16 v[62:65], v[152:155], v[190:193], v[62:65]
	v_mfma_f32_16x16x32_bf16 v[58:61], v[160:163], v[190:193], v[58:61]
	v_mfma_f32_16x16x32_bf16 v[46:49], v[152:155], v[198:201], v[46:49]
	v_mfma_f32_16x16x32_bf16 v[42:45], v[160:163], v[198:201], v[42:45]
	v_mfma_f32_16x16x32_bf16 v[30:33], v[152:155], v[206:209], v[30:33]
	v_mfma_f32_16x16x32_bf16 v[26:29], v[160:163], v[206:209], v[26:29]
	v_mfma_f32_16x16x32_bf16 v[14:17], v[152:155], v[214:217], v[14:17]
	v_mfma_f32_16x16x32_bf16 v[10:13], v[160:163], v[214:217], v[10:13]
	v_mfma_f32_16x16x32_bf16 v[62:65], v[156:159], v[194:197], v[62:65]
	v_mfma_f32_16x16x32_bf16 v[58:61], v[164:167], v[194:197], v[58:61]
	v_mfma_f32_16x16x32_bf16 v[46:49], v[156:159], v[202:205], v[46:49]
	v_mfma_f32_16x16x32_bf16 v[42:45], v[164:167], v[202:205], v[42:45]
	v_mfma_f32_16x16x32_bf16 v[30:33], v[156:159], v[210:213], v[30:33]
	v_mfma_f32_16x16x32_bf16 v[26:29], v[164:167], v[210:213], v[26:29]
	v_mfma_f32_16x16x32_bf16 v[14:17], v[156:159], v[224:227], v[14:17]
	v_mfma_f32_16x16x32_bf16 v[10:13], v[164:167], v[224:227], v[10:13]
	v_mfma_f32_16x16x32_bf16 v[54:57], v[168:171], v[190:193], v[54:57]
	v_mfma_f32_16x16x32_bf16 v[50:53], v[182:185], v[190:193], v[50:53]
	v_mfma_f32_16x16x32_bf16 v[38:41], v[168:171], v[198:201], v[38:41]
	v_mfma_f32_16x16x32_bf16 v[34:37], v[182:185], v[198:201], v[34:37]
	v_mfma_f32_16x16x32_bf16 v[22:25], v[168:171], v[206:209], v[22:25]
	v_mfma_f32_16x16x32_bf16 v[18:21], v[182:185], v[206:209], v[18:21]
	v_mfma_f32_16x16x32_bf16 v[6:9], v[168:171], v[214:217], v[6:9]
	v_mfma_f32_16x16x32_bf16 v[2:5], v[182:185], v[214:217], v[2:5]
	v_mfma_f32_16x16x32_bf16 v[54:57], v[172:175], v[194:197], v[54:57]
	v_mfma_f32_16x16x32_bf16 v[50:53], v[186:189], v[194:197], v[50:53]
	v_mfma_f32_16x16x32_bf16 v[38:41], v[172:175], v[202:205], v[38:41]
	v_mfma_f32_16x16x32_bf16 v[34:37], v[186:189], v[202:205], v[34:37]
	v_mfma_f32_16x16x32_bf16 v[22:25], v[172:175], v[210:213], v[22:25]
	v_mfma_f32_16x16x32_bf16 v[18:21], v[186:189], v[210:213], v[18:21]
	v_mfma_f32_16x16x32_bf16 v[6:9], v[172:175], v[224:227], v[6:9]
	v_mfma_f32_16x16x32_bf16 v[2:5], v[186:189], v[224:227], v[2:5]
	s_barrier
	s_add_i32 s48, 0, 0x18000
	s_add_i32 s91, 0, 0x1c000
	v_add_u32_e32 v164, s48, v179
	v_add_u32_e32 v186, s91, v179
	ds_read_b128 v[152:155], v164
	ds_read_b128 v[156:159], v164 offset:1024
	ds_read_b128 v[160:163], v164 offset:2048
	ds_read_b128 v[164:167], v164 offset:3072
	ds_read_b128 v[168:171], v186
	ds_read_b128 v[172:175], v186 offset:1024
	ds_read_b128 v[182:185], v186 offset:2048
	ds_read_b128 v[186:189], v186 offset:3072
	s_add_u32 s30, s30, 0x80000
	s_addc_u32 s31, s31, 0
	s_mov_b32 m0, s82
	v_lshl_add_u64 v[228:229], s[30:31], 0, v[0:1]
	ds_read_b128 v[190:193], v181 offset:32768
	ds_read_b128 v[194:197], v181 offset:33792
	ds_read_b128 v[198:201], v181 offset:34816
	ds_read_b128 v[202:205], v181 offset:35840
	ds_read_b128 v[206:209], v181 offset:36864
	ds_read_b128 v[210:213], v181 offset:37888
	ds_read_b128 v[214:217], v181 offset:38912
	ds_read_b128 v[224:227], v181 offset:39936
	global_load_lds_dwordx4 v[228:229], off
	s_mov_b32 m0, s83
	v_lshl_add_u64 v[228:229], s[30:31], 0, v[126:127]
	global_load_lds_dwordx4 v[228:229], off
	s_waitcnt vmcnt(8) lgkmcnt(0)
	s_barrier
	v_mfma_f32_16x16x32_bf16 v[74:77], v[152:155], v[190:193], v[74:77]
	v_mfma_f32_16x16x32_bf16 v[78:81], v[160:163], v[190:193], v[78:81]
	v_mfma_f32_16x16x32_bf16 v[102:105], v[152:155], v[198:201], v[102:105]
	v_mfma_f32_16x16x32_bf16 v[106:109], v[160:163], v[198:201], v[106:109]
	v_mfma_f32_16x16x32_bf16 v[122:125], v[152:155], v[206:209], v[122:125]
	v_mfma_f32_16x16x32_bf16 v[144:147], v[160:163], v[206:209], v[144:147]
	v_mfma_f32_16x16x32_bf16 v[90:93], v[152:155], v[214:217], v[90:93]
	v_mfma_f32_16x16x32_bf16 v[86:89], v[160:163], v[214:217], v[86:89]
	v_mfma_f32_16x16x32_bf16 v[74:77], v[156:159], v[194:197], v[74:77]
	v_mfma_f32_16x16x32_bf16 v[78:81], v[164:167], v[194:197], v[78:81]
	v_mfma_f32_16x16x32_bf16 v[102:105], v[156:159], v[202:205], v[102:105]
	v_mfma_f32_16x16x32_bf16 v[106:109], v[164:167], v[202:205], v[106:109]
	v_mfma_f32_16x16x32_bf16 v[122:125], v[156:159], v[210:213], v[122:125]
	v_mfma_f32_16x16x32_bf16 v[144:147], v[164:167], v[210:213], v[144:147]
	v_mfma_f32_16x16x32_bf16 v[90:93], v[156:159], v[224:227], v[90:93]
	v_mfma_f32_16x16x32_bf16 v[86:89], v[164:167], v[224:227], v[86:89]
	v_mfma_f32_16x16x32_bf16 v[82:85], v[168:171], v[190:193], v[82:85]
	v_mfma_f32_16x16x32_bf16 v[94:97], v[182:185], v[190:193], v[94:97]
	v_mfma_f32_16x16x32_bf16 v[110:113], v[168:171], v[198:201], v[110:113]
	v_mfma_f32_16x16x32_bf16 v[118:121], v[182:185], v[198:201], v[118:121]
	v_mfma_f32_16x16x32_bf16 v[114:117], v[168:171], v[206:209], v[114:117]
	v_mfma_f32_16x16x32_bf16 v[98:101], v[182:185], v[206:209], v[98:101]
	v_mfma_f32_16x16x32_bf16 v[70:73], v[168:171], v[214:217], v[70:73]
	v_mfma_f32_16x16x32_bf16 v[66:69], v[182:185], v[214:217], v[66:69]
	v_mfma_f32_16x16x32_bf16 v[82:85], v[172:175], v[194:197], v[82:85]
	v_mfma_f32_16x16x32_bf16 v[94:97], v[186:189], v[194:197], v[94:97]
	v_mfma_f32_16x16x32_bf16 v[110:113], v[172:175], v[202:205], v[110:113]
	v_mfma_f32_16x16x32_bf16 v[118:121], v[186:189], v[202:205], v[118:121]
	v_mfma_f32_16x16x32_bf16 v[114:117], v[172:175], v[210:213], v[114:117]
	v_mfma_f32_16x16x32_bf16 v[98:101], v[186:189], v[210:213], v[98:101]
	v_mfma_f32_16x16x32_bf16 v[70:73], v[172:175], v[224:227], v[70:73]
	v_mfma_f32_16x16x32_bf16 v[66:69], v[186:189], v[224:227], v[66:69]
	s_barrier
; #define PG8_STAGE(bufoff, gbase, voff) do { _Pragma("unroll") for (int _i = 0; _i < 2; ++_i) \
;         __builtin_amdgcn_global_load_lds((const unsigned*)((const char*)(gbase) + (voff)[_i]), (PG8_LAS unsigned*)(lds + (bufoff) + ldsw + _i * 8192), 16, 0, 0); } while (0)
; #define PG8_LDA(dst, b, h) do { _Pragma("unroll") for (int m = 0; m < 4; ++m) _Pragma("unroll") for (int k = 0; k < 2; ++k) dst[m][k] = *(const PG8_LAS bf16x8*)(lds + PG8_SA(b, h) + aoff + m * 2048 + k * 1024); } while (0)
; #define PG8_MMA(ai, bj, At, Bt) do { __builtin_amdgcn_s_setprio(1); _Pragma("unroll") for (int m = 0; m < 4; ++m) _Pragma("unroll") for (int n = 0; n < 2; ++n) _Pragma("unroll") for (int k = 0; k < 2; ++k) \
;         acc[ai][bj][m][n] = __builtin_amdgcn_mfma_f32_16x16x32_bf16(Bt[n][k], At[m][k], acc[ai][bj][m][n], 0, 0, 0); __builtin_amdgcn_s_setprio(0); } while (0)
; #define PG8_WAIT_V(n) asm volatile("s_waitcnt vmcnt(" #n ")" ::: "memory")
; #define PG8_WAIT_L(n) asm volatile("s_waitcnt lgkmcnt(" #n ")" ::: "memory")
; #define PG8_BAR __builtin_amdgcn_s_barrier()
; #define PG8_SCHED __builtin_amdgcn_sched_barrier(0)
; template <class Epi, class Sched, bool ALIGN_EPI = false, bool SP2 = false>
; __device__ __forceinline__ void gemm_phase(PG8_LAS unsigned char* lds, const Gemm g, const Sched& S, const Epi& E) {
;     ...
;         for (int t = 0; t < nt; t += 2) {
;     ...
;             PG8_WAIT_V(8); PG8_WAIT_L(0); PG8_BAR; PG8_MMA(0, 0, At, B0); PG8_MMA(0, 1, At, B1); PG8_BAR; PG8_SCHED;
;             PG8_LDA(At, 1, 1); PG8_STAGE(PG8_SB(1, 0), b3, voffB); PG8_STAGE(PG8_SB(1, 1), b3 + hstep, voffB); PG8_STAGE(PG8_SA(1, 0), a3, voffA);
;             PG8_WAIT_V(8); PG8_WAIT_L(0); PG8_BAR; PG8_MMA(1, 0, At, B0); PG8_MMA(1, 1, At, B1); PG8_BAR; PG8_SCHED;
	s_add_i32 s30, s48, s42
	v_lshl_add_u64 v[176:177], v[176:177], 0, s[64:65]
	s_mov_b32 m0, s30
	ds_read_b128 v[190:193], v181 offset:49152
	ds_read_b128 v[194:197], v181 offset:50176
	ds_read_b128 v[198:201], v181 offset:51200
	ds_read_b128 v[202:205], v181 offset:52224
	ds_read_b128 v[206:209], v181 offset:53248
	ds_read_b128 v[210:213], v181 offset:54272
	ds_read_b128 v[214:217], v181 offset:55296
	ds_read_b128 v[224:227], v181 offset:56320
	global_load_lds_dwordx4 v[176:177], off
	s_add_i32 m0, s30, 0x2000
	s_add_u32 s28, s28, 0x80080
	v_lshl_add_u64 v[176:177], v[218:219], 0, s[64:65]
	s_addc_u32 s29, s29, 0
	s_add_i32 s30, s91, s42
	global_load_lds_dwordx4 v[176:177], off
	s_mov_b32 m0, s30
	v_lshl_add_u64 v[176:177], s[28:29], 0, v[0:1]
	global_load_lds_dwordx4 v[176:177], off
	s_add_i32 m0, s30, 0x2000
	v_lshl_add_u64 v[176:177], s[28:29], 0, v[126:127]
	global_load_lds_dwordx4 v[176:177], off
	s_mov_b32 m0, s86
	v_lshl_add_u64 v[176:177], v[220:221], 0, s[64:65]
	global_load_lds_dwordx4 v[176:177], off
	s_mov_b32 m0, s87
	v_lshl_add_u64 v[176:177], v[222:223], 0, s[64:65]
	global_load_lds_dwordx4 v[176:177], off
	s_waitcnt vmcnt(8) lgkmcnt(0)
	s_barrier
	v_mfma_f32_16x16x32_bf16 v[62:65], v[152:155], v[190:193], v[62:65]
	v_mfma_f32_16x16x32_bf16 v[58:61], v[160:163], v[190:193], v[58:61]
	v_mfma_f32_16x16x32_bf16 v[46:49], v[152:155], v[198:201], v[46:49]
	v_mfma_f32_16x16x32_bf16 v[42:45], v[160:163], v[198:201], v[42:45]
	v_mfma_f32_16x16x32_bf16 v[30:33], v[152:155], v[206:209], v[30:33]
	v_mfma_f32_16x16x32_bf16 v[26:29], v[160:163], v[206:209], v[26:29]
	v_mfma_f32_16x16x32_bf16 v[14:17], v[152:155], v[214:217], v[14:17]
	v_mfma_f32_16x16x32_bf16 v[10:13], v[160:163], v[214:217], v[10:13]
	v_mfma_f32_16x16x32_bf16 v[62:65], v[156:159], v[194:197], v[62:65]
	v_mfma_f32_16x16x32_bf16 v[58:61], v[164:167], v[194:197], v[58:61]
	v_mfma_f32_16x16x32_bf16 v[46:49], v[156:159], v[202:205], v[46:49]
	v_mfma_f32_16x16x32_bf16 v[42:45], v[164:167], v[202:205], v[42:45]
	v_mfma_f32_16x16x32_bf16 v[30:33], v[156:159], v[210:213], v[30:33]
	v_mfma_f32_16x16x32_bf16 v[26:29], v[164:167], v[210:213], v[26:29]
	v_mfma_f32_16x16x32_bf16 v[14:17], v[156:159], v[224:227], v[14:17]
	v_mfma_f32_16x16x32_bf16 v[10:13], v[164:167], v[224:227], v[10:13]
	v_mfma_f32_16x16x32_bf16 v[54:57], v[168:171], v[190:193], v[54:57]
	v_mfma_f32_16x16x32_bf16 v[50:53], v[182:185], v[190:193], v[50:53]
	v_mfma_f32_16x16x32_bf16 v[38:41], v[168:171], v[198:201], v[38:41]
	v_mfma_f32_16x16x32_bf16 v[34:37], v[182:185], v[198:201], v[34:37]
	v_mfma_f32_16x16x32_bf16 v[22:25], v[168:171], v[206:209], v[22:25]
	v_mfma_f32_16x16x32_bf16 v[18:21], v[182:185], v[206:209], v[18:21]
	v_mfma_f32_16x16x32_bf16 v[6:9], v[168:171], v[214:217], v[6:9]
	v_mfma_f32_16x16x32_bf16 v[2:5], v[182:185], v[214:217], v[2:5]
	v_mfma_f32_16x16x32_bf16 v[54:57], v[172:175], v[194:197], v[54:57]
	v_mfma_f32_16x16x32_bf16 v[50:53], v[186:189], v[194:197], v[50:53]
	v_mfma_f32_16x16x32_bf16 v[38:41], v[172:175], v[202:205], v[38:41]
	v_mfma_f32_16x16x32_bf16 v[34:37], v[186:189], v[202:205], v[34:37]
	v_mfma_f32_16x16x32_bf16 v[22:25], v[172:175], v[210:213], v[22:25]
	v_mfma_f32_16x16x32_bf16 v[18:21], v[186:189], v[210:213], v[18:21]
	v_mfma_f32_16x16x32_bf16 v[6:9], v[172:175], v[224:227], v[6:9]
	v_mfma_f32_16x16x32_bf16 v[2:5], v[186:189], v[224:227], v[2:5]
	s_barrier
	s_add_i32 s81, s81, 2
	s_add_u32 s0, s0, 0x100
	s_addc_u32 s1, s1, 0
	s_add_u32 s41, s41, 0x100
	s_addc_u32 s67, s67, 0
	s_cmp_gt_u32 s81, 29
	s_cbranch_scc0 .LBB0_910
	s_and_b64 vcc, exec, s[18:19]
	s_cbranch_vccz .LBB0_913
	s_barrier

; #define PG8_STAGE(bufoff, gbase, voff) do { _Pragma("unroll") for (int _i = 0; _i < 2; ++_i) \
;         __builtin_amdgcn_global_load_lds((const unsigned*)((const char*)(gbase) + (voff)[_i]), (PG8_LAS unsigned*)(lds + (bufoff) + ldsw + _i * 8192), 16, 0, 0); } while (0)
; #define PG8_LDA(dst, b, h) do { _Pragma("unroll") for (int m = 0; m < 4; ++m) _Pragma("unroll") for (int k = 0; k < 2; ++k) dst[m][k] = *(const PG8_LAS bf16x8*)(lds + PG8_SA(b, h) + aoff + m * 2048 + k * 1024); } while (0)
; #define PG8_LDB(dst, b, h) do { _Pragma("unroll") for (int n = 0; n < 2; ++n) _Pragma("unroll") for (int k = 0; k < 2; ++k) dst[n][k] = *(const PG8_LAS bf16x8*)(lds + PG8_SB(b, h) + boff + n * 2048 + k * 1024); } while (0)
; #define PG8_MMA(ai, bj, At, Bt) do { __builtin_amdgcn_s_setprio(1); _Pragma("unroll") for (int m = 0; m < 4; ++m) _Pragma("unroll") for (int n = 0; n < 2; ++n) _Pragma("unroll") for (int k = 0; k < 2; ++k) \
;         acc[ai][bj][m][n] = __builtin_amdgcn_mfma_f32_16x16x32_bf16(Bt[n][k], At[m][k], acc[ai][bj][m][n], 0, 0, 0); __builtin_amdgcn_s_setprio(0); } while (0)
; #define PG8_WAIT_V(n) asm volatile("s_waitcnt vmcnt(" #n ")" ::: "memory")
; #define PG8_WAIT_L(n) asm volatile("s_waitcnt lgkmcnt(" #n ")" ::: "memory")
; #define PG8_BAR __builtin_amdgcn_s_barrier()
; template <class Epi, class Sched, bool ALIGN_EPI = false, bool SP2 = false>
; __device__ __forceinline__ void gemm_phase(PG8_LAS unsigned char* lds, const Gemm g, const Sched& S, const Epi& E) {
;     ...
;             const char* a1 = cA + (size_t)(t + 1) * kstep;
;             const char* a2 = last ? nA : cA + (size_t)(t + 2) * kstep; const char* b2 = last ? nB : cB + (size_t)(t + 2) * kstep;
;             const char* a3 = a2 + kstep; const char* b3 = b2 + kstep;
;             if (last && has_next) S.a_ready(nxt);
;             if constexpr (SP2) {
;             PG8_LDB(B0, 0, 0); PG8_LDB(B1, 0, 1); PG8_SCHED; PG8_LDA(At, 0, 0); PG8_STAGE(PG8_SA(1, 1), a1 + hstep, voffA);
;             PG8_WAIT_V(8); PG8_WAIT_L(0); PG8_BAR; PG8_MMA(0, 0, At, B0); PG8_MMA(0, 1, At, B1); PG8_BAR; PG8_SCHED;
;             PG8_LDA(At, 0, 1); PG8_STAGE(PG8_SB(0, 0), b2, voffB); PG8_STAGE(PG8_SB(0, 1), b2 + hstep, voffB); PG8_STAGE(PG8_SA(0, 0), a2, voffA);
;             PG8_WAIT_V(8); PG8_WAIT_L(0); PG8_BAR; PG8_MMA(1, 0, At, B0); PG8_MMA(1, 1, At, B1); PG8_BAR; PG8_SCHED;
.LBB0_963:
	s_add_u32 s24, s0, 0xfff80080
	s_addc_u32 s25, s1, -1
	s_add_i32 s43, 0, 0x10000
	s_cmp_eq_u32 s42, 28
	s_cselect_b32 s27, s13, s25
	s_cselect_b32 s26, s17, s24
	s_cselect_b32 s25, s19, s41
	s_cselect_b32 s24, s29, s40
	s_add_i32 s48, 0, 0x14000
	v_add_u32_e32 v164, s43, v197
	v_add_u32_e32 v180, s48, v197
	ds_read_b128 v[152:155], v164
	ds_read_b128 v[156:159], v164 offset:1024
	ds_read_b128 v[160:163], v164 offset:2048
	ds_read_b128 v[164:167], v164 offset:3072
	ds_read_b128 v[168:171], v180
	ds_read_b128 v[172:175], v180 offset:1024
	ds_read_b128 v[176:179], v180 offset:2048
	ds_read_b128 v[180:183], v180 offset:3072
	v_lshl_add_u64 v[220:221], s[0:1], 0, v[148:149]
	s_add_i32 m0, s31, 0xc000
	ds_read_b128 v[184:187], v199
	ds_read_b128 v[188:191], v199 offset:1024
	ds_read_b128 v[192:195], v199 offset:2048
	ds_read_b128 v[200:203], v199 offset:3072
	ds_read_b128 v[204:207], v199 offset:4096
	ds_read_b128 v[208:211], v199 offset:5120
	ds_read_b128 v[212:215], v199 offset:6144
	ds_read_b128 v[216:219], v199 offset:7168
	global_load_lds_dwordx4 v[220:221], off
	s_add_i32 m0, s31, 0xe000
	v_lshl_add_u64 v[220:221], s[0:1], 0, v[150:151]
	global_load_lds_dwordx4 v[220:221], off
	s_waitcnt vmcnt(8) lgkmcnt(0)
	s_barrier
	v_mfma_f32_16x16x32_bf16 v[144:147], v[152:155], v[184:187], v[144:147]
	v_mfma_f32_16x16x32_bf16 v[122:125], v[160:163], v[184:187], v[122:125]
	v_mfma_f32_16x16x32_bf16 v[110:113], v[152:155], v[192:195], v[110:113]
	v_mfma_f32_16x16x32_bf16 v[106:109], v[160:163], v[192:195], v[106:109]
	v_mfma_f32_16x16x32_bf16 v[94:97], v[152:155], v[204:207], v[94:97]
	v_mfma_f32_16x16x32_bf16 v[90:93], v[160:163], v[204:207], v[90:93]
	v_mfma_f32_16x16x32_bf16 v[78:81], v[152:155], v[212:215], v[78:81]
	v_mfma_f32_16x16x32_bf16 v[74:77], v[160:163], v[212:215], v[74:77]
	v_mfma_f32_16x16x32_bf16 v[144:147], v[156:159], v[188:191], v[144:147]
	v_mfma_f32_16x16x32_bf16 v[122:125], v[164:167], v[188:191], v[122:125]
	v_mfma_f32_16x16x32_bf16 v[110:113], v[156:159], v[200:203], v[110:113]
	v_mfma_f32_16x16x32_bf16 v[106:109], v[164:167], v[200:203], v[106:109]
	v_mfma_f32_16x16x32_bf16 v[94:97], v[156:159], v[208:211], v[94:97]
	v_mfma_f32_16x16x32_bf16 v[90:93], v[164:167], v[208:211], v[90:93]
	v_mfma_f32_16x16x32_bf16 v[78:81], v[156:159], v[216:219], v[78:81]
	v_mfma_f32_16x16x32_bf16 v[74:77], v[164:167], v[216:219], v[74:77]
	v_mfma_f32_16x16x32_bf16 v[118:121], v[168:171], v[184:187], v[118:121]
	v_mfma_f32_16x16x32_bf16 v[114:117], v[176:179], v[184:187], v[114:117]
	v_mfma_f32_16x16x32_bf16 v[102:105], v[168:171], v[192:195], v[102:105]
	v_mfma_f32_16x16x32_bf16 v[98:101], v[176:179], v[192:195], v[98:101]
	v_mfma_f32_16x16x32_bf16 v[86:89], v[168:171], v[204:207], v[86:89]
	v_mfma_f32_16x16x32_bf16 v[82:85], v[176:179], v[204:207], v[82:85]
	v_mfma_f32_16x16x32_bf16 v[70:73], v[168:171], v[212:215], v[70:73]
	v_mfma_f32_16x16x32_bf16 v[66:69], v[176:179], v[212:215], v[66:69]
	v_mfma_f32_16x16x32_bf16 v[118:121], v[172:175], v[188:191], v[118:121]
	v_mfma_f32_16x16x32_bf16 v[114:117], v[180:183], v[188:191], v[114:117]
	v_mfma_f32_16x16x32_bf16 v[102:105], v[172:175], v[200:203], v[102:105]
	v_mfma_f32_16x16x32_bf16 v[98:101], v[180:183], v[200:203], v[98:101]
	v_mfma_f32_16x16x32_bf16 v[86:89], v[172:175], v[208:211], v[86:89]
	v_mfma_f32_16x16x32_bf16 v[82:85], v[180:183], v[208:211], v[82:85]
	v_mfma_f32_16x16x32_bf16 v[70:73], v[172:175], v[216:219], v[70:73]
	v_mfma_f32_16x16x32_bf16 v[66:69], v[180:183], v[216:219], v[66:69]
	s_barrier
	s_add_i32 s43, s43, s30
	v_lshl_add_u64 v[220:221], s[24:25], 0, v[0:1]
	s_mov_b32 m0, s43
	ds_read_b128 v[184:187], v199 offset:16384
	ds_read_b128 v[188:191], v199 offset:17408
	ds_read_b128 v[192:195], v199 offset:18432
	ds_read_b128 v[200:203], v199 offset:19456
	ds_read_b128 v[204:207], v199 offset:20480
	ds_read_b128 v[208:211], v199 offset:21504
	ds_read_b128 v[212:215], v199 offset:22528
	ds_read_b128 v[216:219], v199 offset:23552
	global_load_lds_dwordx4 v[220:221], off
	s_add_i32 m0, s43, 0x2000
	s_add_u32 vcc_lo, s24, 0x80000
	v_lshl_add_u64 v[222:223], s[24:25], 0, v[126:127]
	s_addc_u32 vcc_hi, s25, 0
	s_add_i32 s43, s48, s30
	global_load_lds_dwordx4 v[222:223], off
	v_lshl_add_u64 v[224:225], vcc, 0, v[0:1]
	s_mov_b32 m0, s43
	v_lshl_add_u64 v[226:227], s[26:27], 0, v[126:127]
	global_load_lds_dwordx4 v[224:225], off
	s_add_i32 m0, s43, 0x2000
	v_lshl_add_u64 v[224:225], vcc, 0, v[126:127]
	global_load_lds_dwordx4 v[224:225], off
	s_mov_b32 m0, s31
	v_lshl_add_u64 v[224:225], s[26:27], 0, v[0:1]
	global_load_lds_dwordx4 v[224:225], off
	s_mov_b32 m0, s34
	s_nop 0
	global_load_lds_dwordx4 v[226:227], off
	s_waitcnt vmcnt(8) lgkmcnt(0)
	s_barrier
; #define PG8_STAGE(bufoff, gbase, voff) do { _Pragma("unroll") for (int _i = 0; _i < 2; ++_i) \
;         __builtin_amdgcn_global_load_lds((const unsigned*)((const char*)(gbase) + (voff)[_i]), (PG8_LAS unsigned*)(lds + (bufoff) + ldsw + _i * 8192), 16, 0, 0); } while (0)
; #define PG8_LDA(dst, b, h) do { _Pragma("unroll") for (int m = 0; m < 4; ++m) _Pragma("unroll") for (int k = 0; k < 2; ++k) dst[m][k] = *(const PG8_LAS bf16x8*)(lds + PG8_SA(b, h) + aoff + m * 2048 + k * 1024); } while (0)
; #define PG8_LDB(dst, b, h) do { _Pragma("unroll") for (int n = 0; n < 2; ++n) _Pragma("unroll") for (int k = 0; k < 2; ++k) dst[n][k] = *(const PG8_LAS bf16x8*)(lds + PG8_SB(b, h) + boff + n * 2048 + k * 1024); } while (0)
; #define PG8_MMA(ai, bj, At, Bt) do { __builtin_amdgcn_s_setprio(1); _Pragma("unroll") for (int m = 0; m < 4; ++m) _Pragma("unroll") for (int n = 0; n < 2; ++n) _Pragma("unroll") for (int k = 0; k < 2; ++k) \
;         acc[ai][bj][m][n] = __builtin_amdgcn_mfma_f32_16x16x32_bf16(Bt[n][k], At[m][k], acc[ai][bj][m][n], 0, 0, 0); __builtin_amdgcn_s_setprio(0); } while (0)
; #define PG8_WAIT_V(n) asm volatile("s_waitcnt vmcnt(" #n ")" ::: "memory")
; #define PG8_WAIT_L(n) asm volatile("s_waitcnt lgkmcnt(" #n ")" ::: "memory")
; #define PG8_BAR __builtin_amdgcn_s_barrier()
; #define PG8_SCHED __builtin_amdgcn_sched_barrier(0)
; template <class Epi, class Sched, bool ALIGN_EPI = false, bool SP2 = false>
; __device__ __forceinline__ void gemm_phase(PG8_LAS unsigned char* lds, const Gemm g, const Sched& S, const Epi& E) {
;     ...
;             PG8_WAIT_V(8); PG8_WAIT_L(0); PG8_BAR; PG8_MMA(1, 0, At, B0); PG8_MMA(1, 1, At, B1); PG8_BAR; PG8_SCHED;
;             PG8_LDB(B0, 1, 0); PG8_LDB(B1, 1, 1); PG8_SCHED; PG8_LDA(At, 1, 0); PG8_STAGE(PG8_SA(0, 1), a2 + hstep, voffA);
;             PG8_WAIT_V(8); PG8_WAIT_L(0); PG8_BAR; PG8_MMA(0, 0, At, B0); PG8_MMA(0, 1, At, B1); PG8_BAR; PG8_SCHED;
	v_mfma_f32_16x16x32_bf16 v[62:65], v[152:155], v[184:187], v[62:65]
	v_mfma_f32_16x16x32_bf16 v[58:61], v[160:163], v[184:187], v[58:61]
	v_mfma_f32_16x16x32_bf16 v[46:49], v[152:155], v[192:195], v[46:49]
	v_mfma_f32_16x16x32_bf16 v[42:45], v[160:163], v[192:195], v[42:45]
	v_mfma_f32_16x16x32_bf16 v[30:33], v[152:155], v[204:207], v[30:33]
	v_mfma_f32_16x16x32_bf16 v[26:29], v[160:163], v[204:207], v[26:29]
	v_mfma_f32_16x16x32_bf16 v[14:17], v[152:155], v[212:215], v[14:17]
	v_mfma_f32_16x16x32_bf16 v[10:13], v[160:163], v[212:215], v[10:13]
	v_mfma_f32_16x16x32_bf16 v[62:65], v[156:159], v[188:191], v[62:65]
	v_mfma_f32_16x16x32_bf16 v[58:61], v[164:167], v[188:191], v[58:61]
	v_mfma_f32_16x16x32_bf16 v[46:49], v[156:159], v[200:203], v[46:49]
	v_mfma_f32_16x16x32_bf16 v[42:45], v[164:167], v[200:203], v[42:45]
	v_mfma_f32_16x16x32_bf16 v[30:33], v[156:159], v[208:211], v[30:33]
	v_mfma_f32_16x16x32_bf16 v[26:29], v[164:167], v[208:211], v[26:29]
	v_mfma_f32_16x16x32_bf16 v[14:17], v[156:159], v[216:219], v[14:17]
	v_mfma_f32_16x16x32_bf16 v[10:13], v[164:167], v[216:219], v[10:13]
	v_mfma_f32_16x16x32_bf16 v[54:57], v[168:171], v[184:187], v[54:57]
	v_mfma_f32_16x16x32_bf16 v[50:53], v[176:179], v[184:187], v[50:53]
	v_mfma_f32_16x16x32_bf16 v[38:41], v[168:171], v[192:195], v[38:41]
	v_mfma_f32_16x16x32_bf16 v[34:37], v[176:179], v[192:195], v[34:37]
	v_mfma_f32_16x16x32_bf16 v[22:25], v[168:171], v[204:207], v[22:25]
	v_mfma_f32_16x16x32_bf16 v[18:21], v[176:179], v[204:207], v[18:21]
	v_mfma_f32_16x16x32_bf16 v[6:9], v[168:171], v[212:215], v[6:9]
	v_mfma_f32_16x16x32_bf16 v[2:5], v[176:179], v[212:215], v[2:5]
	v_mfma_f32_16x16x32_bf16 v[54:57], v[172:175], v[188:191], v[54:57]
	v_mfma_f32_16x16x32_bf16 v[50:53], v[180:183], v[188:191], v[50:53]
	v_mfma_f32_16x16x32_bf16 v[38:41], v[172:175], v[200:203], v[38:41]
	v_mfma_f32_16x16x32_bf16 v[34:37], v[180:183], v[200:203], v[34:37]
	v_mfma_f32_16x16x32_bf16 v[22:25], v[172:175], v[208:211], v[22:25]
	v_mfma_f32_16x16x32_bf16 v[18:21], v[180:183], v[208:211], v[18:21]
	v_mfma_f32_16x16x32_bf16 v[6:9], v[172:175], v[216:219], v[6:9]
	v_mfma_f32_16x16x32_bf16 v[2:5], v[180:183], v[216:219], v[2:5]
	s_barrier
	s_add_i32 s43, 0, 0x18000
	s_add_i32 s48, 0, 0x1c000
	v_add_u32_e32 v164, s43, v197
	v_add_u32_e32 v180, s48, v197
	ds_read_b128 v[152:155], v164
	ds_read_b128 v[156:159], v164 offset:1024
	ds_read_b128 v[160:163], v164 offset:2048
	ds_read_b128 v[164:167], v164 offset:3072
	ds_read_b128 v[168:171], v180
	ds_read_b128 v[172:175], v180 offset:1024
	ds_read_b128 v[176:179], v180 offset:2048
	ds_read_b128 v[180:183], v180 offset:3072
	s_add_u32 s26, s26, 0x80000
	s_addc_u32 s27, s27, 0
	s_mov_b32 m0, s35
	v_lshl_add_u64 v[228:229], s[26:27], 0, v[0:1]
	ds_read_b128 v[184:187], v199 offset:32768
	ds_read_b128 v[188:191], v199 offset:33792
	ds_read_b128 v[192:195], v199 offset:34816
	ds_read_b128 v[200:203], v199 offset:35840
	ds_read_b128 v[204:207], v199 offset:36864
	ds_read_b128 v[208:211], v199 offset:37888
	ds_read_b128 v[212:215], v199 offset:38912
	ds_read_b128 v[216:219], v199 offset:39936
	global_load_lds_dwordx4 v[228:229], off
	s_mov_b32 m0, s76
	v_lshl_add_u64 v[228:229], s[26:27], 0, v[126:127]
	global_load_lds_dwordx4 v[228:229], off
	s_waitcnt vmcnt(8) lgkmcnt(0)
	s_barrier
	v_mfma_f32_16x16x32_bf16 v[144:147], v[152:155], v[184:187], v[144:147]
	v_mfma_f32_16x16x32_bf16 v[122:125], v[160:163], v[184:187], v[122:125]
	v_mfma_f32_16x16x32_bf16 v[110:113], v[152:155], v[192:195], v[110:113]
	v_mfma_f32_16x16x32_bf16 v[106:109], v[160:163], v[192:195], v[106:109]
	v_mfma_f32_16x16x32_bf16 v[94:97], v[152:155], v[204:207], v[94:97]
	v_mfma_f32_16x16x32_bf16 v[90:93], v[160:163], v[204:207], v[90:93]
	v_mfma_f32_16x16x32_bf16 v[78:81], v[152:155], v[212:215], v[78:81]
	v_mfma_f32_16x16x32_bf16 v[74:77], v[160:163], v[212:215], v[74:77]
	v_mfma_f32_16x16x32_bf16 v[144:147], v[156:159], v[188:191], v[144:147]
	v_mfma_f32_16x16x32_bf16 v[122:125], v[164:167], v[188:191], v[122:125]
	v_mfma_f32_16x16x32_bf16 v[110:113], v[156:159], v[200:203], v[110:113]
	v_mfma_f32_16x16x32_bf16 v[106:109], v[164:167], v[200:203], v[106:109]
	v_mfma_f32_16x16x32_bf16 v[94:97], v[156:159], v[208:211], v[94:97]
	v_mfma_f32_16x16x32_bf16 v[90:93], v[164:167], v[208:211], v[90:93]
	v_mfma_f32_16x16x32_bf16 v[78:81], v[156:159], v[216:219], v[78:81]
	v_mfma_f32_16x16x32_bf16 v[74:77], v[164:167], v[216:219], v[74:77]
	v_mfma_f32_16x16x32_bf16 v[118:121], v[168:171], v[184:187], v[118:121]
	v_mfma_f32_16x16x32_bf16 v[114:117], v[176:179], v[184:187], v[114:117]
	v_mfma_f32_16x16x32_bf16 v[102:105], v[168:171], v[192:195], v[102:105]
	v_mfma_f32_16x16x32_bf16 v[98:101], v[176:179], v[192:195], v[98:101]
	v_mfma_f32_16x16x32_bf16 v[86:89], v[168:171], v[204:207], v[86:89]
	v_mfma_f32_16x16x32_bf16 v[82:85], v[176:179], v[204:207], v[82:85]
	v_mfma_f32_16x16x32_bf16 v[70:73], v[168:171], v[212:215], v[70:73]
	v_mfma_f32_16x16x32_bf16 v[66:69], v[176:179], v[212:215], v[66:69]
	v_mfma_f32_16x16x32_bf16 v[118:121], v[172:175], v[188:191], v[118:121]
	v_mfma_f32_16x16x32_bf16 v[114:117], v[180:183], v[188:191], v[114:117]
	v_mfma_f32_16x16x32_bf16 v[102:105], v[172:175], v[200:203], v[102:105]
	v_mfma_f32_16x16x32_bf16 v[98:101], v[180:183], v[200:203], v[98:101]
	v_mfma_f32_16x16x32_bf16 v[86:89], v[172:175], v[208:211], v[86:89]
	v_mfma_f32_16x16x32_bf16 v[82:85], v[180:183], v[208:211], v[82:85]
	v_mfma_f32_16x16x32_bf16 v[70:73], v[172:175], v[216:219], v[70:73]
	v_mfma_f32_16x16x32_bf16 v[66:69], v[180:183], v[216:219], v[66:69]
	s_barrier
; #define PG8_STAGE(bufoff, gbase, voff) do { _Pragma("unroll") for (int _i = 0; _i < 2; ++_i) \
;         __builtin_amdgcn_global_load_lds((const unsigned*)((const char*)(gbase) + (voff)[_i]), (PG8_LAS unsigned*)(lds + (bufoff) + ldsw + _i * 8192), 16, 0, 0); } while (0)
; #define PG8_LDA(dst, b, h) do { _Pragma("unroll") for (int m = 0; m < 4; ++m) _Pragma("unroll") for (int k = 0; k < 2; ++k) dst[m][k] = *(const PG8_LAS bf16x8*)(lds + PG8_SA(b, h) + aoff + m * 2048 + k * 1024); } while (0)
; #define PG8_MMA(ai, bj, At, Bt) do { __builtin_amdgcn_s_setprio(1); _Pragma("unroll") for (int m = 0; m < 4; ++m) _Pragma("unroll") for (int n = 0; n < 2; ++n) _Pragma("unroll") for (int k = 0; k < 2; ++k) \
;         acc[ai][bj][m][n] = __builtin_amdgcn_mfma_f32_16x16x32_bf16(Bt[n][k], At[m][k], acc[ai][bj][m][n], 0, 0, 0); __builtin_amdgcn_s_setprio(0); } while (0)
; #define PG8_WAIT_V(n) asm volatile("s_waitcnt vmcnt(" #n ")" ::: "memory")
; #define PG8_WAIT_L(n) asm volatile("s_waitcnt lgkmcnt(" #n ")" ::: "memory")
; #define PG8_BAR __builtin_amdgcn_s_barrier()
; #define PG8_SCHED __builtin_amdgcn_sched_barrier(0)
; template <class Epi, class Sched, bool ALIGN_EPI = false, bool SP2 = false>
; __device__ __forceinline__ void gemm_phase(PG8_LAS unsigned char* lds, const Gemm g, const Sched& S, const Epi& E) {
;     ...
;             PG8_LDA(At, 1, 1); PG8_STAGE(PG8_SB(1, 0), b3, voffB); PG8_STAGE(PG8_SB(1, 1), b3 + hstep, voffB); PG8_STAGE(PG8_SA(1, 0), a3, voffA);
;             PG8_WAIT_V(8); PG8_WAIT_L(0); PG8_BAR; PG8_MMA(1, 0, At, B0); PG8_MMA(1, 1, At, B1); PG8_BAR; PG8_SCHED;
;     ...
;         if constexpr (ALIGN_EPI) { if (wr == 0) PG8_BAR; }
	s_add_i32 s26, s43, s30
	v_lshl_add_u64 v[220:221], v[220:221], 0, s[64:65]
	s_mov_b32 m0, s26
	ds_read_b128 v[184:187], v199 offset:49152
	ds_read_b128 v[188:191], v199 offset:50176
	ds_read_b128 v[192:195], v199 offset:51200
	ds_read_b128 v[200:203], v199 offset:52224
	ds_read_b128 v[204:207], v199 offset:53248
	ds_read_b128 v[208:211], v199 offset:54272
	ds_read_b128 v[212:215], v199 offset:55296
	ds_read_b128 v[216:219], v199 offset:56320
	global_load_lds_dwordx4 v[220:221], off
	s_add_i32 m0, s26, 0x2000
	s_add_u32 s24, s24, 0x80080
	v_lshl_add_u64 v[220:221], v[222:223], 0, s[64:65]
	s_addc_u32 s25, s25, 0
	s_add_i32 s26, s48, s30
	global_load_lds_dwordx4 v[220:221], off
	s_mov_b32 m0, s26
	v_lshl_add_u64 v[220:221], s[24:25], 0, v[0:1]
	global_load_lds_dwordx4 v[220:221], off
	s_add_i32 m0, s26, 0x2000
	v_lshl_add_u64 v[220:221], s[24:25], 0, v[126:127]
	global_load_lds_dwordx4 v[220:221], off
	s_mov_b32 m0, s82
	v_lshl_add_u64 v[220:221], v[224:225], 0, s[64:65]
	global_load_lds_dwordx4 v[220:221], off
	s_mov_b32 m0, s83
	v_lshl_add_u64 v[220:221], v[226:227], 0, s[64:65]
	global_load_lds_dwordx4 v[220:221], off
	s_waitcnt vmcnt(8) lgkmcnt(0)
	s_barrier
	v_mfma_f32_16x16x32_bf16 v[62:65], v[152:155], v[184:187], v[62:65]
	v_mfma_f32_16x16x32_bf16 v[58:61], v[160:163], v[184:187], v[58:61]
	v_mfma_f32_16x16x32_bf16 v[46:49], v[152:155], v[192:195], v[46:49]
	v_mfma_f32_16x16x32_bf16 v[42:45], v[160:163], v[192:195], v[42:45]
	v_mfma_f32_16x16x32_bf16 v[30:33], v[152:155], v[204:207], v[30:33]
	v_mfma_f32_16x16x32_bf16 v[26:29], v[160:163], v[204:207], v[26:29]
	v_mfma_f32_16x16x32_bf16 v[14:17], v[152:155], v[212:215], v[14:17]
	v_mfma_f32_16x16x32_bf16 v[10:13], v[160:163], v[212:215], v[10:13]
	v_mfma_f32_16x16x32_bf16 v[62:65], v[156:159], v[188:191], v[62:65]
	v_mfma_f32_16x16x32_bf16 v[58:61], v[164:167], v[188:191], v[58:61]
	v_mfma_f32_16x16x32_bf16 v[46:49], v[156:159], v[200:203], v[46:49]
	v_mfma_f32_16x16x32_bf16 v[42:45], v[164:167], v[200:203], v[42:45]
	v_mfma_f32_16x16x32_bf16 v[30:33], v[156:159], v[208:211], v[30:33]
	v_mfma_f32_16x16x32_bf16 v[26:29], v[164:167], v[208:211], v[26:29]
	v_mfma_f32_16x16x32_bf16 v[14:17], v[156:159], v[216:219], v[14:17]
	v_mfma_f32_16x16x32_bf16 v[10:13], v[164:167], v[216:219], v[10:13]
	v_mfma_f32_16x16x32_bf16 v[54:57], v[168:171], v[184:187], v[54:57]
	v_mfma_f32_16x16x32_bf16 v[50:53], v[176:179], v[184:187], v[50:53]
	v_mfma_f32_16x16x32_bf16 v[38:41], v[168:171], v[192:195], v[38:41]
	v_mfma_f32_16x16x32_bf16 v[34:37], v[176:179], v[192:195], v[34:37]
	v_mfma_f32_16x16x32_bf16 v[22:25], v[168:171], v[204:207], v[22:25]
	v_mfma_f32_16x16x32_bf16 v[18:21], v[176:179], v[204:207], v[18:21]
	v_mfma_f32_16x16x32_bf16 v[6:9], v[168:171], v[212:215], v[6:9]
	v_mfma_f32_16x16x32_bf16 v[2:5], v[176:179], v[212:215], v[2:5]
	v_mfma_f32_16x16x32_bf16 v[54:57], v[172:175], v[188:191], v[54:57]
	v_mfma_f32_16x16x32_bf16 v[50:53], v[180:183], v[188:191], v[50:53]
	v_mfma_f32_16x16x32_bf16 v[38:41], v[172:175], v[200:203], v[38:41]
	v_mfma_f32_16x16x32_bf16 v[34:37], v[180:183], v[200:203], v[34:37]
	v_mfma_f32_16x16x32_bf16 v[22:25], v[172:175], v[208:211], v[22:25]
	v_mfma_f32_16x16x32_bf16 v[18:21], v[180:183], v[208:211], v[18:21]
	v_mfma_f32_16x16x32_bf16 v[6:9], v[172:175], v[216:219], v[6:9]
	v_mfma_f32_16x16x32_bf16 v[2:5], v[180:183], v[216:219], v[2:5]
	s_barrier
	s_add_i32 s42, s42, 2
	s_add_u32 s0, s0, 0x100
	s_addc_u32 s1, s1, 0
	s_add_u32 s40, s40, 0x100
	s_addc_u32 s41, s41, 0
	s_cmp_gt_u32 s42, 29
	s_cbranch_scc0 .LBB0_963
	s_and_b64 vcc, exec, s[14:15]
	s_cbranch_vccz .LBB0_966
	s_barrier
